# MFMA issue order within each 16-MFMA block snaked (A operand held across B change) in all four GEMM K-loops
# speedup vs baseline: 1.0167x; 1.0079x over previous
; #define PG8_STAGE(bufoff, gbase, voff) do { _Pragma("unroll") for (int _i = 0; _i < 2; ++_i) \
;         __builtin_amdgcn_global_load_lds((const unsigned*)((const char*)(gbase) + (voff)[_i]), (PG8_LAS unsigned*)(lds + (bufoff) + ldsw + _i * 8192), 16, 0, 0); } while (0)
; #define PG8_LDA(dst, b, h) do { _Pragma("unroll") for (int m = 0; m < 4; ++m) _Pragma("unroll") for (int k = 0; k < 2; ++k) dst[m][k] = *(const PG8_LAS bf16x8*)(lds + PG8_SA(b, h) + aoff + m * 2048 + k * 1024); } while (0)
; #define PG8_LDB(dst, b, h) do { _Pragma("unroll") for (int n = 0; n < 2; ++n) _Pragma("unroll") for (int k = 0; k < 2; ++k) dst[n][k] = *(const PG8_LAS bf16x8*)(lds + PG8_SB(b, h) + boff + n * 2048 + k * 1024); } while (0)
; #define PG8_MMA(ai, bj, At, Bt) do { __builtin_amdgcn_s_setprio(1); _Pragma("unroll") for (int m = 0; m < 4; ++m) _Pragma("unroll") for (int n = 0; n < 2; ++n) _Pragma("unroll") for (int k = 0; k < 2; ++k) \
;         acc[ai][bj][m][n] = __builtin_amdgcn_mfma_f32_16x16x32_bf16(Bt[n][k], At[m][k], acc[ai][bj][m][n], 0, 0, 0); __builtin_amdgcn_s_setprio(0); } while (0)
; #define PG8_WAIT_V(n) asm volatile("s_waitcnt vmcnt(" #n ")" ::: "memory")
; #define PG8_WAIT_L(n) asm volatile("s_waitcnt lgkmcnt(" #n ")" ::: "memory")
; #define PG8_BAR __builtin_amdgcn_s_barrier()
; #define PG8_SCHED __builtin_amdgcn_sched_barrier(0)
; template <class Epi, class Sched, bool ALIGN_EPI = false, bool SP2 = false>
; __device__ __forceinline__ void gemm_phase(PG8_LAS unsigned char* lds, const Gemm g, const Sched& S, const Epi& E) {
;     ...
;             PG8_LDB(B0, 0, 0); PG8_LDB(B1, 0, 1); PG8_SCHED; PG8_LDA(At, 0, 0); PG8_STAGE(PG8_SA(1, 1), a1 + hstep, voffA);
;             PG8_WAIT_V(8); PG8_WAIT_L(0); PG8_BAR; PG8_MMA(0, 0, At, B0); PG8_MMA(0, 1, At, B1); PG8_BAR; PG8_SCHED;
;             PG8_LDA(At, 0, 1); PG8_STAGE(PG8_SB(0, 0), b2, voffB); PG8_STAGE(PG8_SB(0, 1), b2 + hstepB, voffB); PG8_STAGE(PG8_SA(0, 0), a2, voffA);
;             PG8_WAIT_V(8); PG8_WAIT_L(0); PG8_BAR; PG8_MMA(1, 0, At, B0); PG8_MMA(1, 1, At, B1); PG8_BAR; PG8_SCHED;
.LBB0_402:
	ds_read_b128 v[82:85], v178
	ds_read_b128 v[86:89], v178 offset:1024
	ds_read_b128 v[90:93], v178 offset:2048
	ds_read_b128 v[94:97], v178 offset:3072
	ds_read_b128 v[186:189], v179
	ds_read_b128 v[190:193], v179 offset:1024
	ds_read_b128 v[194:197], v179 offset:2048
	ds_read_b128 v[198:201], v179 offset:3072
	s_add_u32 s10, s6, 0xfff00080
	s_addc_u32 s11, s7, -1
	s_cmp_eq_u32 s51, 60
	s_cselect_b32 s35, s23, s11
	s_cselect_b32 s34, s47, s10
	s_cselect_b32 s11, s21, s50
	s_cselect_b32 s10, s48, s49
	v_lshl_add_u64 v[234:235], s[6:7], 0, v[158:159]
	s_add_i32 m0, s29, 0xc000
	ds_read_b128 v[202:205], v180
	ds_read_b128 v[206:209], v180 offset:1024
	ds_read_b128 v[210:213], v180 offset:2048
	ds_read_b128 v[214:217], v180 offset:3072
	ds_read_b128 v[218:221], v180 offset:4096
	ds_read_b128 v[222:225], v180 offset:5120
	ds_read_b128 v[226:229], v180 offset:6144
	ds_read_b128 v[230:233], v180 offset:7168
	global_load_lds_dwordx4 v[234:235], off
	v_lshl_add_u64 v[234:235], s[6:7], 0, v[160:161]
	s_add_i32 m0, s29, 0xe000
	s_nop 0
	global_load_lds_dwordx4 v[234:235], off
	s_waitcnt vmcnt(8)
	s_waitcnt lgkmcnt(0)
	s_barrier
	s_setprio 1
	s_waitcnt lgkmcnt(0)
	v_mfma_f32_16x16x32_bf16 v[142:145], v[82:85], v[202:205], v[142:145]
	v_mfma_f32_16x16x32_bf16 v[138:141], v[90:93], v[202:205], v[138:141]
	v_mfma_f32_16x16x32_bf16 v[122:125], v[90:93], v[210:213], v[122:125]
	v_mfma_f32_16x16x32_bf16 v[126:129], v[82:85], v[210:213], v[126:129]
	v_mfma_f32_16x16x32_bf16 v[110:113], v[82:85], v[218:221], v[110:113]
	v_mfma_f32_16x16x32_bf16 v[106:109], v[90:93], v[218:221], v[106:109]
	v_mfma_f32_16x16x32_bf16 v[74:77], v[90:93], v[226:229], v[74:77]
	v_mfma_f32_16x16x32_bf16 v[78:81], v[82:85], v[226:229], v[78:81]
	v_mfma_f32_16x16x32_bf16 v[142:145], v[86:89], v[206:209], v[142:145]
	v_mfma_f32_16x16x32_bf16 v[138:141], v[94:97], v[206:209], v[138:141]
	v_mfma_f32_16x16x32_bf16 v[122:125], v[94:97], v[214:217], v[122:125]
	v_mfma_f32_16x16x32_bf16 v[126:129], v[86:89], v[214:217], v[126:129]
	v_mfma_f32_16x16x32_bf16 v[110:113], v[86:89], v[222:225], v[110:113]
	v_mfma_f32_16x16x32_bf16 v[106:109], v[94:97], v[222:225], v[106:109]
	v_mfma_f32_16x16x32_bf16 v[74:77], v[94:97], v[230:233], v[74:77]
	v_mfma_f32_16x16x32_bf16 v[78:81], v[86:89], v[230:233], v[78:81]
	s_setprio 0
	s_setprio 1
	v_mfma_f32_16x16x32_bf16 v[134:137], v[186:189], v[202:205], v[134:137]
	v_mfma_f32_16x16x32_bf16 v[130:133], v[194:197], v[202:205], v[130:133]
	v_mfma_f32_16x16x32_bf16 v[114:117], v[194:197], v[210:213], v[114:117]
	v_mfma_f32_16x16x32_bf16 v[118:121], v[186:189], v[210:213], v[118:121]
	v_mfma_f32_16x16x32_bf16 v[102:105], v[186:189], v[218:221], v[102:105]
	v_mfma_f32_16x16x32_bf16 v[98:101], v[194:197], v[218:221], v[98:101]
	v_mfma_f32_16x16x32_bf16 v[66:69], v[194:197], v[226:229], v[66:69]
	v_mfma_f32_16x16x32_bf16 v[70:73], v[186:189], v[226:229], v[70:73]
	v_mfma_f32_16x16x32_bf16 v[134:137], v[190:193], v[206:209], v[134:137]
	v_mfma_f32_16x16x32_bf16 v[130:133], v[198:201], v[206:209], v[130:133]
	v_mfma_f32_16x16x32_bf16 v[114:117], v[198:201], v[214:217], v[114:117]
	v_mfma_f32_16x16x32_bf16 v[118:121], v[190:193], v[214:217], v[118:121]
	v_mfma_f32_16x16x32_bf16 v[102:105], v[190:193], v[222:225], v[102:105]
	v_mfma_f32_16x16x32_bf16 v[98:101], v[198:201], v[222:225], v[98:101]
	v_mfma_f32_16x16x32_bf16 v[66:69], v[198:201], v[230:233], v[66:69]
	v_mfma_f32_16x16x32_bf16 v[70:73], v[190:193], v[230:233], v[70:73]
	s_setprio 0
	s_barrier
	s_add_i32 s52, s42, s37
	v_lshl_add_u64 v[234:235], s[10:11], 0, v[148:149]
	s_mov_b32 m0, s52
	ds_read_b128 v[202:205], v180 offset:16384
	ds_read_b128 v[206:209], v180 offset:17408
	ds_read_b128 v[210:213], v180 offset:18432
	ds_read_b128 v[214:217], v180 offset:19456
	ds_read_b128 v[218:221], v180 offset:20480
	ds_read_b128 v[222:225], v180 offset:21504
	ds_read_b128 v[226:229], v180 offset:22528
	ds_read_b128 v[230:233], v180 offset:23552
	global_load_lds_dwordx4 v[234:235], off
	s_add_i32 m0, s52, 0x2000
	s_add_u32 s52, s10, 0x40000
	v_lshl_add_u64 v[236:237], s[10:11], 0, v[152:153]
	s_addc_u32 s53, s11, 0
	s_add_i32 s54, s43, s37
	global_load_lds_dwordx4 v[236:237], off
	v_lshl_add_u64 v[238:239], s[52:53], 0, v[148:149]
	s_mov_b32 m0, s54
	v_lshl_add_u64 v[240:241], s[34:35], 0, v[150:151]
	global_load_lds_dwordx4 v[238:239], off
	v_lshl_add_u64 v[238:239], s[52:53], 0, v[152:153]
	s_add_i32 m0, s54, 0x2000
	s_nop 0
	global_load_lds_dwordx4 v[238:239], off
	v_lshl_add_u64 v[238:239], s[34:35], 0, v[146:147]
	s_mov_b32 m0, s29
	s_nop 0
	global_load_lds_dwordx4 v[238:239], off
	s_mov_b32 m0, s31
	s_nop 0
	global_load_lds_dwordx4 v[240:241], off
	s_waitcnt vmcnt(8)
	s_waitcnt lgkmcnt(0)
	s_barrier
; #define PG8_STAGE(bufoff, gbase, voff) do { _Pragma("unroll") for (int _i = 0; _i < 2; ++_i) \
;         __builtin_amdgcn_global_load_lds((const unsigned*)((const char*)(gbase) + (voff)[_i]), (PG8_LAS unsigned*)(lds + (bufoff) + ldsw + _i * 8192), 16, 0, 0); } while (0)
; #define PG8_LDA(dst, b, h) do { _Pragma("unroll") for (int m = 0; m < 4; ++m) _Pragma("unroll") for (int k = 0; k < 2; ++k) dst[m][k] = *(const PG8_LAS bf16x8*)(lds + PG8_SA(b, h) + aoff + m * 2048 + k * 1024); } while (0)
; #define PG8_LDB(dst, b, h) do { _Pragma("unroll") for (int n = 0; n < 2; ++n) _Pragma("unroll") for (int k = 0; k < 2; ++k) dst[n][k] = *(const PG8_LAS bf16x8*)(lds + PG8_SB(b, h) + boff + n * 2048 + k * 1024); } while (0)
; #define PG8_MMA(ai, bj, At, Bt) do { __builtin_amdgcn_s_setprio(1); _Pragma("unroll") for (int m = 0; m < 4; ++m) _Pragma("unroll") for (int n = 0; n < 2; ++n) _Pragma("unroll") for (int k = 0; k < 2; ++k) \
;         acc[ai][bj][m][n] = __builtin_amdgcn_mfma_f32_16x16x32_bf16(Bt[n][k], At[m][k], acc[ai][bj][m][n], 0, 0, 0); __builtin_amdgcn_s_setprio(0); } while (0)
; #define PG8_WAIT_V(n) asm volatile("s_waitcnt vmcnt(" #n ")" ::: "memory")
; #define PG8_WAIT_L(n) asm volatile("s_waitcnt lgkmcnt(" #n ")" ::: "memory")
; #define PG8_BAR __builtin_amdgcn_s_barrier()
; #define PG8_SCHED __builtin_amdgcn_sched_barrier(0)
; template <class Epi, class Sched, bool ALIGN_EPI = false, bool SP2 = false>
; __device__ __forceinline__ void gemm_phase(PG8_LAS unsigned char* lds, const Gemm g, const Sched& S, const Epi& E) {
;     ...
;             PG8_WAIT_V(8); PG8_WAIT_L(0); PG8_BAR; PG8_MMA(1, 0, At, B0); PG8_MMA(1, 1, At, B1); PG8_BAR; PG8_SCHED;
;             PG8_LDB(B0, 1, 0); PG8_LDB(B1, 1, 1); PG8_SCHED; PG8_LDA(At, 1, 0); PG8_STAGE(PG8_SA(0, 1), a2 + hstep, voffA);
;             PG8_WAIT_V(8); PG8_WAIT_L(0); PG8_BAR; PG8_MMA(0, 0, At, B0); PG8_MMA(0, 1, At, B1); PG8_BAR; PG8_SCHED;
	s_setprio 1
	s_waitcnt lgkmcnt(0)
	v_mfma_f32_16x16x32_bf16 v[62:65], v[82:85], v[202:205], v[62:65]
	v_mfma_f32_16x16x32_bf16 v[58:61], v[90:93], v[202:205], v[58:61]
	v_mfma_f32_16x16x32_bf16 v[42:45], v[90:93], v[210:213], v[42:45]
	v_mfma_f32_16x16x32_bf16 v[46:49], v[82:85], v[210:213], v[46:49]
	v_mfma_f32_16x16x32_bf16 v[30:33], v[82:85], v[218:221], v[30:33]
	v_mfma_f32_16x16x32_bf16 v[26:29], v[90:93], v[218:221], v[26:29]
	v_mfma_f32_16x16x32_bf16 v[10:13], v[90:93], v[226:229], v[10:13]
	v_mfma_f32_16x16x32_bf16 v[14:17], v[82:85], v[226:229], v[14:17]
	v_mfma_f32_16x16x32_bf16 v[62:65], v[86:89], v[206:209], v[62:65]
	v_mfma_f32_16x16x32_bf16 v[58:61], v[94:97], v[206:209], v[58:61]
	v_mfma_f32_16x16x32_bf16 v[42:45], v[94:97], v[214:217], v[42:45]
	v_mfma_f32_16x16x32_bf16 v[46:49], v[86:89], v[214:217], v[46:49]
	v_mfma_f32_16x16x32_bf16 v[30:33], v[86:89], v[222:225], v[30:33]
	v_mfma_f32_16x16x32_bf16 v[26:29], v[94:97], v[222:225], v[26:29]
	v_mfma_f32_16x16x32_bf16 v[10:13], v[94:97], v[230:233], v[10:13]
	v_mfma_f32_16x16x32_bf16 v[14:17], v[86:89], v[230:233], v[14:17]
	s_setprio 0
	s_setprio 1
	v_mfma_f32_16x16x32_bf16 v[54:57], v[186:189], v[202:205], v[54:57]
	v_mfma_f32_16x16x32_bf16 v[50:53], v[194:197], v[202:205], v[50:53]
	v_mfma_f32_16x16x32_bf16 v[34:37], v[194:197], v[210:213], v[34:37]
	v_mfma_f32_16x16x32_bf16 v[38:41], v[186:189], v[210:213], v[38:41]
	v_mfma_f32_16x16x32_bf16 v[22:25], v[186:189], v[218:221], v[22:25]
	v_mfma_f32_16x16x32_bf16 v[18:21], v[194:197], v[218:221], v[18:21]
	v_mfma_f32_16x16x32_bf16 v[2:5], v[194:197], v[226:229], v[2:5]
	v_mfma_f32_16x16x32_bf16 v[6:9], v[186:189], v[226:229], v[6:9]
	v_mfma_f32_16x16x32_bf16 v[54:57], v[190:193], v[206:209], v[54:57]
	v_mfma_f32_16x16x32_bf16 v[50:53], v[198:201], v[206:209], v[50:53]
	v_mfma_f32_16x16x32_bf16 v[34:37], v[198:201], v[214:217], v[34:37]
	v_mfma_f32_16x16x32_bf16 v[38:41], v[190:193], v[214:217], v[38:41]
	v_mfma_f32_16x16x32_bf16 v[22:25], v[190:193], v[222:225], v[22:25]
	v_mfma_f32_16x16x32_bf16 v[18:21], v[198:201], v[222:225], v[18:21]
	v_mfma_f32_16x16x32_bf16 v[2:5], v[198:201], v[230:233], v[2:5]
	v_mfma_f32_16x16x32_bf16 v[6:9], v[190:193], v[230:233], v[6:9]
	s_setprio 0
	s_barrier
	s_add_i32 s52, 0, 0x18000
	s_add_i32 s53, 0, 0x1c000
	v_add_u32_e32 v94, s52, v1
	v_add_u32_e32 v167, s53, v1
	ds_read_b128 v[82:85], v94
	ds_read_b128 v[86:89], v94 offset:1024
	ds_read_b128 v[90:93], v94 offset:2048
	ds_read_b128 v[94:97], v94 offset:3072
	ds_read_b128 v[186:189], v167
	ds_read_b128 v[190:193], v167 offset:1024
	ds_read_b128 v[194:197], v167 offset:2048
	ds_read_b128 v[198:201], v167 offset:3072
	s_add_u32 s34, s34, 0x100000
	s_addc_u32 s35, s35, 0
	s_mov_b32 m0, s38
	v_lshl_add_u64 v[242:243], s[34:35], 0, v[146:147]
	ds_read_b128 v[202:205], v180 offset:32768
	ds_read_b128 v[206:209], v180 offset:33792
	ds_read_b128 v[210:213], v180 offset:34816
	ds_read_b128 v[214:217], v180 offset:35840
	ds_read_b128 v[218:221], v180 offset:36864
	ds_read_b128 v[222:225], v180 offset:37888
	ds_read_b128 v[226:229], v180 offset:38912
	ds_read_b128 v[230:233], v180 offset:39936
	global_load_lds_dwordx4 v[242:243], off
	v_lshl_add_u64 v[242:243], s[34:35], 0, v[150:151]
	s_mov_b32 m0, s39
	s_nop 0
	global_load_lds_dwordx4 v[242:243], off
	s_waitcnt vmcnt(8)
	s_waitcnt lgkmcnt(0)
	s_barrier
	s_setprio 1
	s_waitcnt lgkmcnt(0)
	v_mfma_f32_16x16x32_bf16 v[142:145], v[82:85], v[202:205], v[142:145]
	v_mfma_f32_16x16x32_bf16 v[138:141], v[90:93], v[202:205], v[138:141]
	v_mfma_f32_16x16x32_bf16 v[122:125], v[90:93], v[210:213], v[122:125]
	v_mfma_f32_16x16x32_bf16 v[126:129], v[82:85], v[210:213], v[126:129]
	v_mfma_f32_16x16x32_bf16 v[110:113], v[82:85], v[218:221], v[110:113]
	v_mfma_f32_16x16x32_bf16 v[106:109], v[90:93], v[218:221], v[106:109]
	v_mfma_f32_16x16x32_bf16 v[74:77], v[90:93], v[226:229], v[74:77]
	v_mfma_f32_16x16x32_bf16 v[78:81], v[82:85], v[226:229], v[78:81]
	v_mfma_f32_16x16x32_bf16 v[142:145], v[86:89], v[206:209], v[142:145]
	v_mfma_f32_16x16x32_bf16 v[138:141], v[94:97], v[206:209], v[138:141]
	v_mfma_f32_16x16x32_bf16 v[122:125], v[94:97], v[214:217], v[122:125]
	v_mfma_f32_16x16x32_bf16 v[126:129], v[86:89], v[214:217], v[126:129]
	v_mfma_f32_16x16x32_bf16 v[110:113], v[86:89], v[222:225], v[110:113]
	v_mfma_f32_16x16x32_bf16 v[106:109], v[94:97], v[222:225], v[106:109]
	v_mfma_f32_16x16x32_bf16 v[74:77], v[94:97], v[230:233], v[74:77]
	v_mfma_f32_16x16x32_bf16 v[78:81], v[86:89], v[230:233], v[78:81]
	s_setprio 0
	s_setprio 1
	v_mfma_f32_16x16x32_bf16 v[134:137], v[186:189], v[202:205], v[134:137]
	v_mfma_f32_16x16x32_bf16 v[130:133], v[194:197], v[202:205], v[130:133]
	v_mfma_f32_16x16x32_bf16 v[114:117], v[194:197], v[210:213], v[114:117]
	v_mfma_f32_16x16x32_bf16 v[118:121], v[186:189], v[210:213], v[118:121]
	v_mfma_f32_16x16x32_bf16 v[102:105], v[186:189], v[218:221], v[102:105]
	v_mfma_f32_16x16x32_bf16 v[98:101], v[194:197], v[218:221], v[98:101]
	v_mfma_f32_16x16x32_bf16 v[66:69], v[194:197], v[226:229], v[66:69]
	v_mfma_f32_16x16x32_bf16 v[70:73], v[186:189], v[226:229], v[70:73]
	v_mfma_f32_16x16x32_bf16 v[134:137], v[190:193], v[206:209], v[134:137]
	v_mfma_f32_16x16x32_bf16 v[130:133], v[198:201], v[206:209], v[130:133]
	v_mfma_f32_16x16x32_bf16 v[114:117], v[198:201], v[214:217], v[114:117]
	v_mfma_f32_16x16x32_bf16 v[118:121], v[190:193], v[214:217], v[118:121]
	v_mfma_f32_16x16x32_bf16 v[102:105], v[190:193], v[222:225], v[102:105]
	v_mfma_f32_16x16x32_bf16 v[98:101], v[198:201], v[222:225], v[98:101]
	v_mfma_f32_16x16x32_bf16 v[66:69], v[198:201], v[230:233], v[66:69]
	v_mfma_f32_16x16x32_bf16 v[70:73], v[190:193], v[230:233], v[70:73]
	s_setprio 0
	s_barrier
; #define PG8_STAGE(bufoff, gbase, voff) do { _Pragma("unroll") for (int _i = 0; _i < 2; ++_i) \
;         __builtin_amdgcn_global_load_lds((const unsigned*)((const char*)(gbase) + (voff)[_i]), (PG8_LAS unsigned*)(lds + (bufoff) + ldsw + _i * 8192), 16, 0, 0); } while (0)
; #define PG8_LDA(dst, b, h) do { _Pragma("unroll") for (int m = 0; m < 4; ++m) _Pragma("unroll") for (int k = 0; k < 2; ++k) dst[m][k] = *(const PG8_LAS bf16x8*)(lds + PG8_SA(b, h) + aoff + m * 2048 + k * 1024); } while (0)
; #define PG8_MMA(ai, bj, At, Bt) do { __builtin_amdgcn_s_setprio(1); _Pragma("unroll") for (int m = 0; m < 4; ++m) _Pragma("unroll") for (int n = 0; n < 2; ++n) _Pragma("unroll") for (int k = 0; k < 2; ++k) \
;         acc[ai][bj][m][n] = __builtin_amdgcn_mfma_f32_16x16x32_bf16(Bt[n][k], At[m][k], acc[ai][bj][m][n], 0, 0, 0); __builtin_amdgcn_s_setprio(0); } while (0)
; #define PG8_WAIT_V(n) asm volatile("s_waitcnt vmcnt(" #n ")" ::: "memory")
; #define PG8_WAIT_L(n) asm volatile("s_waitcnt lgkmcnt(" #n ")" ::: "memory")
; #define PG8_BAR __builtin_amdgcn_s_barrier()
; #define PG8_SCHED __builtin_amdgcn_sched_barrier(0)
; template <class Epi, class Sched, bool ALIGN_EPI = false, bool SP2 = false>
; __device__ __forceinline__ void gemm_phase(PG8_LAS unsigned char* lds, const Gemm g, const Sched& S, const Epi& E) {
;     ...
;             PG8_LDA(At, 1, 1); PG8_STAGE(PG8_SB(1, 0), b3, voffB); PG8_STAGE(PG8_SB(1, 1), b3 + hstepB, voffB); PG8_STAGE(PG8_SA(1, 0), a3, voffA);
;             PG8_WAIT_V(8); PG8_WAIT_L(0); PG8_BAR; PG8_MMA(1, 0, At, B0); PG8_MMA(1, 1, At, B1); PG8_BAR; PG8_SCHED;
	s_add_i32 s34, s52, s37
	v_lshl_add_u64 v[234:235], v[234:235], 0, s[16:17]
	s_mov_b32 m0, s34
	ds_read_b128 v[202:205], v180 offset:49152
	ds_read_b128 v[206:209], v180 offset:50176
	ds_read_b128 v[210:213], v180 offset:51200
	ds_read_b128 v[214:217], v180 offset:52224
	ds_read_b128 v[218:221], v180 offset:53248
	ds_read_b128 v[222:225], v180 offset:54272
	ds_read_b128 v[226:229], v180 offset:55296
	ds_read_b128 v[230:233], v180 offset:56320
	global_load_lds_dwordx4 v[234:235], off
	s_add_i32 m0, s34, 0x2000
	s_add_u32 s10, s10, 0x40080
	v_lshl_add_u64 v[234:235], v[236:237], 0, s[16:17]
	s_addc_u32 s11, s11, 0
	s_add_i32 s34, s53, s37
	global_load_lds_dwordx4 v[234:235], off
	v_lshl_add_u64 v[234:235], s[10:11], 0, v[148:149]
	s_mov_b32 m0, s34
	s_nop 0
	global_load_lds_dwordx4 v[234:235], off
	v_lshl_add_u64 v[234:235], s[10:11], 0, v[152:153]
	s_add_i32 m0, s34, 0x2000
	s_nop 0
	global_load_lds_dwordx4 v[234:235], off
	v_lshl_add_u64 v[234:235], v[238:239], 0, s[16:17]
	s_mov_b32 m0, s40
	s_nop 0
	global_load_lds_dwordx4 v[234:235], off
	v_lshl_add_u64 v[234:235], v[240:241], 0, s[16:17]
	s_mov_b32 m0, s41
	s_nop 0
	global_load_lds_dwordx4 v[234:235], off
	s_waitcnt vmcnt(8)
	s_waitcnt lgkmcnt(0)
	s_barrier
	s_setprio 1
	s_waitcnt lgkmcnt(0)
	v_mfma_f32_16x16x32_bf16 v[62:65], v[82:85], v[202:205], v[62:65]
	v_mfma_f32_16x16x32_bf16 v[58:61], v[90:93], v[202:205], v[58:61]
	v_mfma_f32_16x16x32_bf16 v[42:45], v[90:93], v[210:213], v[42:45]
	v_mfma_f32_16x16x32_bf16 v[46:49], v[82:85], v[210:213], v[46:49]
	v_mfma_f32_16x16x32_bf16 v[30:33], v[82:85], v[218:221], v[30:33]
	v_mfma_f32_16x16x32_bf16 v[26:29], v[90:93], v[218:221], v[26:29]
	v_mfma_f32_16x16x32_bf16 v[10:13], v[90:93], v[226:229], v[10:13]
	v_mfma_f32_16x16x32_bf16 v[14:17], v[82:85], v[226:229], v[14:17]
	v_mfma_f32_16x16x32_bf16 v[62:65], v[86:89], v[206:209], v[62:65]
	v_mfma_f32_16x16x32_bf16 v[58:61], v[94:97], v[206:209], v[58:61]
	v_mfma_f32_16x16x32_bf16 v[42:45], v[94:97], v[214:217], v[42:45]
	v_mfma_f32_16x16x32_bf16 v[46:49], v[86:89], v[214:217], v[46:49]
	v_mfma_f32_16x16x32_bf16 v[30:33], v[86:89], v[222:225], v[30:33]
	v_mfma_f32_16x16x32_bf16 v[26:29], v[94:97], v[222:225], v[26:29]
	v_mfma_f32_16x16x32_bf16 v[10:13], v[94:97], v[230:233], v[10:13]
	v_mfma_f32_16x16x32_bf16 v[14:17], v[86:89], v[230:233], v[14:17]
	s_setprio 0
	s_setprio 1
	v_mfma_f32_16x16x32_bf16 v[54:57], v[186:189], v[202:205], v[54:57]
	v_mfma_f32_16x16x32_bf16 v[50:53], v[194:197], v[202:205], v[50:53]
	v_mfma_f32_16x16x32_bf16 v[34:37], v[194:197], v[210:213], v[34:37]
	v_mfma_f32_16x16x32_bf16 v[38:41], v[186:189], v[210:213], v[38:41]
	v_mfma_f32_16x16x32_bf16 v[22:25], v[186:189], v[218:221], v[22:25]
	v_mfma_f32_16x16x32_bf16 v[18:21], v[194:197], v[218:221], v[18:21]
	v_mfma_f32_16x16x32_bf16 v[2:5], v[194:197], v[226:229], v[2:5]
	v_mfma_f32_16x16x32_bf16 v[6:9], v[186:189], v[226:229], v[6:9]
	v_mfma_f32_16x16x32_bf16 v[54:57], v[190:193], v[206:209], v[54:57]
	v_mfma_f32_16x16x32_bf16 v[50:53], v[198:201], v[206:209], v[50:53]
	v_mfma_f32_16x16x32_bf16 v[34:37], v[198:201], v[214:217], v[34:37]
	v_mfma_f32_16x16x32_bf16 v[38:41], v[190:193], v[214:217], v[38:41]
	v_mfma_f32_16x16x32_bf16 v[22:25], v[190:193], v[222:225], v[22:25]
	v_mfma_f32_16x16x32_bf16 v[18:21], v[198:201], v[222:225], v[18:21]
	v_mfma_f32_16x16x32_bf16 v[2:5], v[198:201], v[230:233], v[2:5]
	v_mfma_f32_16x16x32_bf16 v[6:9], v[190:193], v[230:233], v[6:9]
	s_setprio 0
	s_barrier
	s_add_i32 s51, s51, 2
	s_add_u32 s6, s6, 0x100
	s_addc_u32 s7, s7, 0
	s_add_u32 s49, s49, 0x100
	s_addc_u32 s50, s50, 0
	s_cmp_gt_u32 s51, 61
	s_cbranch_scc0 .LBB0_402
	s_and_b64 vcc, exec, s[18:19]
	s_cbranch_vccz .LBB0_405
	s_barrier

; #define PG8_STAGE(bufoff, gbase, voff) do { _Pragma("unroll") for (int _i = 0; _i < 2; ++_i) \
;         __builtin_amdgcn_global_load_lds((const unsigned*)((const char*)(gbase) + (voff)[_i]), (PG8_LAS unsigned*)(lds + (bufoff) + ldsw + _i * 8192), 16, 0, 0); } while (0)
; #define PG8_LDA(dst, b, h) do { _Pragma("unroll") for (int m = 0; m < 4; ++m) _Pragma("unroll") for (int k = 0; k < 2; ++k) dst[m][k] = *(const PG8_LAS bf16x8*)(lds + PG8_SA(b, h) + aoff + m * 2048 + k * 1024); } while (0)
; #define PG8_LDB(dst, b, h) do { _Pragma("unroll") for (int n = 0; n < 2; ++n) _Pragma("unroll") for (int k = 0; k < 2; ++k) dst[n][k] = *(const PG8_LAS bf16x8*)(lds + PG8_SB(b, h) + boff + n * 2048 + k * 1024); } while (0)
; #define PG8_MMA(ai, bj, At, Bt) do { __builtin_amdgcn_s_setprio(1); _Pragma("unroll") for (int m = 0; m < 4; ++m) _Pragma("unroll") for (int n = 0; n < 2; ++n) _Pragma("unroll") for (int k = 0; k < 2; ++k) \
;         acc[ai][bj][m][n] = __builtin_amdgcn_mfma_f32_16x16x32_bf16(Bt[n][k], At[m][k], acc[ai][bj][m][n], 0, 0, 0); __builtin_amdgcn_s_setprio(0); } while (0)
; #define PG8_WAIT_V(n) asm volatile("s_waitcnt vmcnt(" #n ")" ::: "memory")
; #define PG8_WAIT_L(n) asm volatile("s_waitcnt lgkmcnt(" #n ")" ::: "memory")
; #define PG8_BAR __builtin_amdgcn_s_barrier()
; #define PG8_SCHED __builtin_amdgcn_sched_barrier(0)
; template <class Epi, class Sched, bool ALIGN_EPI = false, bool SP2 = false>
; __device__ __forceinline__ void gemm_phase(PG8_LAS unsigned char* lds, const Gemm g, const Sched& S, const Epi& E) {
;     ...
;             PG8_LDB(B0, 0, 0); PG8_LDB(B1, 0, 1); PG8_SCHED; PG8_LDA(At, 0, 0); PG8_STAGE(PG8_SA(1, 1), a1 + hstep, voffA);
;             PG8_WAIT_V(8); PG8_WAIT_L(0); PG8_BAR; PG8_MMA(0, 0, At, B0); PG8_MMA(0, 1, At, B1); PG8_BAR; PG8_SCHED;
;             PG8_LDA(At, 0, 1); PG8_STAGE(PG8_SB(0, 0), b2, voffB); PG8_STAGE(PG8_SB(0, 1), b2 + hstepB, voffB); PG8_STAGE(PG8_SA(0, 0), a2, voffA);
;             PG8_WAIT_V(8); PG8_WAIT_L(0); PG8_BAR; PG8_MMA(1, 0, At, B0); PG8_MMA(1, 1, At, B1); PG8_BAR; PG8_SCHED;
.LBB0_1759:
	ds_read_b128 v[66:69], v168
	ds_read_b128 v[70:73], v168 offset:1024
	ds_read_b128 v[74:77], v168 offset:2048
	ds_read_b128 v[78:81], v168 offset:3072
	ds_read_b128 v[162:165], v169
	ds_read_b128 v[172:175], v169 offset:1024
	ds_read_b128 v[176:179], v169 offset:2048
	ds_read_b128 v[180:183], v169 offset:3072
	s_add_u32 s34, s30, 0xfff00080
	s_addc_u32 s35, s31, -1
	s_cmp_eq_u32 s63, 60
	s_cselect_b32 s37, s23, s35
	s_cselect_b32 s36, s59, s34
	s_cselect_b32 s35, s21, s62
	s_cselect_b32 s34, s60, s61
	v_lshl_add_u64 v[216:217], s[30:31], 0, v[154:155]
	s_add_i32 m0, s40, 0xc000
	ds_read_b128 v[184:187], v170
	ds_read_b128 v[188:191], v170 offset:1024
	ds_read_b128 v[192:195], v170 offset:2048
	ds_read_b128 v[196:199], v170 offset:3072
	ds_read_b128 v[200:203], v170 offset:4096
	ds_read_b128 v[204:207], v170 offset:5120
	ds_read_b128 v[208:211], v170 offset:6144
	ds_read_b128 v[212:215], v170 offset:7168
	global_load_lds_dwordx4 v[216:217], off
	v_lshl_add_u64 v[216:217], s[30:31], 0, v[156:157]
	s_add_i32 m0, s40, 0xe000
	s_nop 0
	global_load_lds_dwordx4 v[216:217], off
	s_waitcnt vmcnt(8)
	s_waitcnt lgkmcnt(0)
	s_barrier
	s_setprio 1
	s_waitcnt lgkmcnt(0)
	v_mfma_f32_16x16x32_bf16 v[142:145], v[66:69], v[184:187], v[142:145]
	v_mfma_f32_16x16x32_bf16 v[138:141], v[74:77], v[184:187], v[138:141]
	v_mfma_f32_16x16x32_bf16 v[122:125], v[74:77], v[192:195], v[122:125]
	v_mfma_f32_16x16x32_bf16 v[126:129], v[66:69], v[192:195], v[126:129]
	v_mfma_f32_16x16x32_bf16 v[110:113], v[66:69], v[200:203], v[110:113]
	v_mfma_f32_16x16x32_bf16 v[106:109], v[74:77], v[200:203], v[106:109]
	v_mfma_f32_16x16x32_bf16 v[90:93], v[74:77], v[208:211], v[90:93]
	v_mfma_f32_16x16x32_bf16 v[94:97], v[66:69], v[208:211], v[94:97]
	v_mfma_f32_16x16x32_bf16 v[142:145], v[70:73], v[188:191], v[142:145]
	v_mfma_f32_16x16x32_bf16 v[138:141], v[78:81], v[188:191], v[138:141]
	v_mfma_f32_16x16x32_bf16 v[122:125], v[78:81], v[196:199], v[122:125]
	v_mfma_f32_16x16x32_bf16 v[126:129], v[70:73], v[196:199], v[126:129]
	v_mfma_f32_16x16x32_bf16 v[110:113], v[70:73], v[204:207], v[110:113]
	v_mfma_f32_16x16x32_bf16 v[106:109], v[78:81], v[204:207], v[106:109]
	v_mfma_f32_16x16x32_bf16 v[90:93], v[78:81], v[212:215], v[90:93]
	v_mfma_f32_16x16x32_bf16 v[94:97], v[70:73], v[212:215], v[94:97]
	s_setprio 0
	s_setprio 1
	v_mfma_f32_16x16x32_bf16 v[134:137], v[162:165], v[184:187], v[134:137]
	v_mfma_f32_16x16x32_bf16 v[130:133], v[176:179], v[184:187], v[130:133]
	v_mfma_f32_16x16x32_bf16 v[114:117], v[176:179], v[192:195], v[114:117]
	v_mfma_f32_16x16x32_bf16 v[118:121], v[162:165], v[192:195], v[118:121]
	v_mfma_f32_16x16x32_bf16 v[102:105], v[162:165], v[200:203], v[102:105]
	v_mfma_f32_16x16x32_bf16 v[98:101], v[176:179], v[200:203], v[98:101]
	v_mfma_f32_16x16x32_bf16 v[82:85], v[176:179], v[208:211], v[82:85]
	v_mfma_f32_16x16x32_bf16 v[86:89], v[162:165], v[208:211], v[86:89]
	v_mfma_f32_16x16x32_bf16 v[134:137], v[172:175], v[188:191], v[134:137]
	v_mfma_f32_16x16x32_bf16 v[130:133], v[180:183], v[188:191], v[130:133]
	v_mfma_f32_16x16x32_bf16 v[114:117], v[180:183], v[196:199], v[114:117]
	v_mfma_f32_16x16x32_bf16 v[118:121], v[172:175], v[196:199], v[118:121]
	v_mfma_f32_16x16x32_bf16 v[102:105], v[172:175], v[204:207], v[102:105]
	v_mfma_f32_16x16x32_bf16 v[98:101], v[180:183], v[204:207], v[98:101]
	v_mfma_f32_16x16x32_bf16 v[82:85], v[180:183], v[212:215], v[82:85]
	v_mfma_f32_16x16x32_bf16 v[86:89], v[172:175], v[212:215], v[86:89]
	s_setprio 0
	s_barrier
	s_add_i32 s64, s50, s39
	v_lshl_add_u64 v[216:217], s[34:35], 0, v[148:149]
	s_mov_b32 m0, s64
	ds_read_b128 v[184:187], v170 offset:16384
	ds_read_b128 v[188:191], v170 offset:17408
	ds_read_b128 v[192:195], v170 offset:18432
	ds_read_b128 v[196:199], v170 offset:19456
	ds_read_b128 v[200:203], v170 offset:20480
	ds_read_b128 v[204:207], v170 offset:21504
	ds_read_b128 v[208:211], v170 offset:22528
	ds_read_b128 v[212:215], v170 offset:23552
	global_load_lds_dwordx4 v[216:217], off
	s_add_i32 m0, s64, 0x2000
	s_add_u32 s64, s34, 0x100000
	v_lshl_add_u64 v[218:219], s[34:35], 0, v[152:153]
	s_addc_u32 s65, s35, 0
	s_add_i32 s66, s51, s39
	global_load_lds_dwordx4 v[218:219], off
	v_lshl_add_u64 v[220:221], s[64:65], 0, v[148:149]
	s_mov_b32 m0, s66
	v_lshl_add_u64 v[222:223], s[36:37], 0, v[150:151]
	global_load_lds_dwordx4 v[220:221], off
	v_lshl_add_u64 v[220:221], s[64:65], 0, v[152:153]
	s_add_i32 m0, s66, 0x2000
	s_nop 0
	global_load_lds_dwordx4 v[220:221], off
	v_lshl_add_u64 v[220:221], s[36:37], 0, v[146:147]
	s_mov_b32 m0, s40
	s_nop 0
	global_load_lds_dwordx4 v[220:221], off
	s_mov_b32 m0, s41
	s_nop 0
	global_load_lds_dwordx4 v[222:223], off
	s_waitcnt vmcnt(8)
	s_waitcnt lgkmcnt(0)
	s_barrier
; #define PG8_STAGE(bufoff, gbase, voff) do { _Pragma("unroll") for (int _i = 0; _i < 2; ++_i) \
;         __builtin_amdgcn_global_load_lds((const unsigned*)((const char*)(gbase) + (voff)[_i]), (PG8_LAS unsigned*)(lds + (bufoff) + ldsw + _i * 8192), 16, 0, 0); } while (0)
; #define PG8_LDA(dst, b, h) do { _Pragma("unroll") for (int m = 0; m < 4; ++m) _Pragma("unroll") for (int k = 0; k < 2; ++k) dst[m][k] = *(const PG8_LAS bf16x8*)(lds + PG8_SA(b, h) + aoff + m * 2048 + k * 1024); } while (0)
; #define PG8_LDB(dst, b, h) do { _Pragma("unroll") for (int n = 0; n < 2; ++n) _Pragma("unroll") for (int k = 0; k < 2; ++k) dst[n][k] = *(const PG8_LAS bf16x8*)(lds + PG8_SB(b, h) + boff + n * 2048 + k * 1024); } while (0)
; #define PG8_MMA(ai, bj, At, Bt) do { __builtin_amdgcn_s_setprio(1); _Pragma("unroll") for (int m = 0; m < 4; ++m) _Pragma("unroll") for (int n = 0; n < 2; ++n) _Pragma("unroll") for (int k = 0; k < 2; ++k) \
;         acc[ai][bj][m][n] = __builtin_amdgcn_mfma_f32_16x16x32_bf16(Bt[n][k], At[m][k], acc[ai][bj][m][n], 0, 0, 0); __builtin_amdgcn_s_setprio(0); } while (0)
; #define PG8_WAIT_V(n) asm volatile("s_waitcnt vmcnt(" #n ")" ::: "memory")
; #define PG8_WAIT_L(n) asm volatile("s_waitcnt lgkmcnt(" #n ")" ::: "memory")
; #define PG8_BAR __builtin_amdgcn_s_barrier()
; #define PG8_SCHED __builtin_amdgcn_sched_barrier(0)
; template <class Epi, class Sched, bool ALIGN_EPI = false, bool SP2 = false>
; __device__ __forceinline__ void gemm_phase(PG8_LAS unsigned char* lds, const Gemm g, const Sched& S, const Epi& E) {
;     ...
;             PG8_WAIT_V(8); PG8_WAIT_L(0); PG8_BAR; PG8_MMA(1, 0, At, B0); PG8_MMA(1, 1, At, B1); PG8_BAR; PG8_SCHED;
;             PG8_LDB(B0, 1, 0); PG8_LDB(B1, 1, 1); PG8_SCHED; PG8_LDA(At, 1, 0); PG8_STAGE(PG8_SA(0, 1), a2 + hstep, voffA);
;             PG8_WAIT_V(8); PG8_WAIT_L(0); PG8_BAR; PG8_MMA(0, 0, At, B0); PG8_MMA(0, 1, At, B1); PG8_BAR; PG8_SCHED;
	s_setprio 1
	s_waitcnt lgkmcnt(0)
	v_mfma_f32_16x16x32_bf16 v[62:65], v[66:69], v[184:187], v[62:65]
	v_mfma_f32_16x16x32_bf16 v[58:61], v[74:77], v[184:187], v[58:61]
	v_mfma_f32_16x16x32_bf16 v[42:45], v[74:77], v[192:195], v[42:45]
	v_mfma_f32_16x16x32_bf16 v[46:49], v[66:69], v[192:195], v[46:49]
	v_mfma_f32_16x16x32_bf16 v[30:33], v[66:69], v[200:203], v[30:33]
	v_mfma_f32_16x16x32_bf16 v[26:29], v[74:77], v[200:203], v[26:29]
	v_mfma_f32_16x16x32_bf16 v[18:21], v[74:77], v[208:211], v[18:21]
	v_mfma_f32_16x16x32_bf16 v[22:25], v[66:69], v[208:211], v[22:25]
	v_mfma_f32_16x16x32_bf16 v[62:65], v[70:73], v[188:191], v[62:65]
	v_mfma_f32_16x16x32_bf16 v[58:61], v[78:81], v[188:191], v[58:61]
	v_mfma_f32_16x16x32_bf16 v[42:45], v[78:81], v[196:199], v[42:45]
	v_mfma_f32_16x16x32_bf16 v[46:49], v[70:73], v[196:199], v[46:49]
	v_mfma_f32_16x16x32_bf16 v[30:33], v[70:73], v[204:207], v[30:33]
	v_mfma_f32_16x16x32_bf16 v[26:29], v[78:81], v[204:207], v[26:29]
	v_mfma_f32_16x16x32_bf16 v[18:21], v[78:81], v[212:215], v[18:21]
	v_mfma_f32_16x16x32_bf16 v[22:25], v[70:73], v[212:215], v[22:25]
	s_setprio 0
	s_setprio 1
	v_mfma_f32_16x16x32_bf16 v[54:57], v[162:165], v[184:187], v[54:57]
	v_mfma_f32_16x16x32_bf16 v[50:53], v[176:179], v[184:187], v[50:53]
	v_mfma_f32_16x16x32_bf16 v[34:37], v[176:179], v[192:195], v[34:37]
	v_mfma_f32_16x16x32_bf16 v[38:41], v[162:165], v[192:195], v[38:41]
	v_mfma_f32_16x16x32_bf16 v[14:17], v[162:165], v[200:203], v[14:17]
	v_mfma_f32_16x16x32_bf16 v[10:13], v[176:179], v[200:203], v[10:13]
	v_mfma_f32_16x16x32_bf16 v[2:5], v[176:179], v[208:211], v[2:5]
	v_mfma_f32_16x16x32_bf16 v[6:9], v[162:165], v[208:211], v[6:9]
	v_mfma_f32_16x16x32_bf16 v[54:57], v[172:175], v[188:191], v[54:57]
	v_mfma_f32_16x16x32_bf16 v[50:53], v[180:183], v[188:191], v[50:53]
	v_mfma_f32_16x16x32_bf16 v[34:37], v[180:183], v[196:199], v[34:37]
	v_mfma_f32_16x16x32_bf16 v[38:41], v[172:175], v[196:199], v[38:41]
	v_mfma_f32_16x16x32_bf16 v[14:17], v[172:175], v[204:207], v[14:17]
	v_mfma_f32_16x16x32_bf16 v[10:13], v[180:183], v[204:207], v[10:13]
	v_mfma_f32_16x16x32_bf16 v[2:5], v[180:183], v[212:215], v[2:5]
	v_mfma_f32_16x16x32_bf16 v[6:9], v[172:175], v[212:215], v[6:9]
	s_setprio 0
	s_barrier
	s_add_i32 s64, 0, 0x18000
	s_add_i32 s65, 0, 0x1c000
	v_add_u32_e32 v78, s64, v166
	v_add_u32_e32 v171, s65, v166
	ds_read_b128 v[66:69], v78
	ds_read_b128 v[70:73], v78 offset:1024
	ds_read_b128 v[74:77], v78 offset:2048
	ds_read_b128 v[78:81], v78 offset:3072
	ds_read_b128 v[162:165], v171
	ds_read_b128 v[172:175], v171 offset:1024
	ds_read_b128 v[176:179], v171 offset:2048
	ds_read_b128 v[180:183], v171 offset:3072
	s_add_u32 s36, s36, 0x100000
	s_addc_u32 s37, s37, 0
	s_mov_b32 m0, s42
	v_lshl_add_u64 v[224:225], s[36:37], 0, v[146:147]
	ds_read_b128 v[184:187], v170 offset:32768
	ds_read_b128 v[188:191], v170 offset:33792
	ds_read_b128 v[192:195], v170 offset:34816
	ds_read_b128 v[196:199], v170 offset:35840
	ds_read_b128 v[200:203], v170 offset:36864
	ds_read_b128 v[204:207], v170 offset:37888
	ds_read_b128 v[208:211], v170 offset:38912
	ds_read_b128 v[212:215], v170 offset:39936
	global_load_lds_dwordx4 v[224:225], off
	v_lshl_add_u64 v[224:225], s[36:37], 0, v[150:151]
	s_mov_b32 m0, s43
	s_nop 0
	global_load_lds_dwordx4 v[224:225], off
	s_waitcnt vmcnt(8)
	s_waitcnt lgkmcnt(0)
	s_barrier
	s_setprio 1
	s_waitcnt lgkmcnt(0)
	v_mfma_f32_16x16x32_bf16 v[142:145], v[66:69], v[184:187], v[142:145]
	v_mfma_f32_16x16x32_bf16 v[138:141], v[74:77], v[184:187], v[138:141]
	v_mfma_f32_16x16x32_bf16 v[122:125], v[74:77], v[192:195], v[122:125]
	v_mfma_f32_16x16x32_bf16 v[126:129], v[66:69], v[192:195], v[126:129]
	v_mfma_f32_16x16x32_bf16 v[110:113], v[66:69], v[200:203], v[110:113]
	v_mfma_f32_16x16x32_bf16 v[106:109], v[74:77], v[200:203], v[106:109]
	v_mfma_f32_16x16x32_bf16 v[90:93], v[74:77], v[208:211], v[90:93]
	v_mfma_f32_16x16x32_bf16 v[94:97], v[66:69], v[208:211], v[94:97]
	v_mfma_f32_16x16x32_bf16 v[142:145], v[70:73], v[188:191], v[142:145]
	v_mfma_f32_16x16x32_bf16 v[138:141], v[78:81], v[188:191], v[138:141]
	v_mfma_f32_16x16x32_bf16 v[122:125], v[78:81], v[196:199], v[122:125]
	v_mfma_f32_16x16x32_bf16 v[126:129], v[70:73], v[196:199], v[126:129]
	v_mfma_f32_16x16x32_bf16 v[110:113], v[70:73], v[204:207], v[110:113]
	v_mfma_f32_16x16x32_bf16 v[106:109], v[78:81], v[204:207], v[106:109]
	v_mfma_f32_16x16x32_bf16 v[90:93], v[78:81], v[212:215], v[90:93]
	v_mfma_f32_16x16x32_bf16 v[94:97], v[70:73], v[212:215], v[94:97]
	s_setprio 0
	s_setprio 1
	v_mfma_f32_16x16x32_bf16 v[134:137], v[162:165], v[184:187], v[134:137]
	v_mfma_f32_16x16x32_bf16 v[130:133], v[176:179], v[184:187], v[130:133]
	v_mfma_f32_16x16x32_bf16 v[114:117], v[176:179], v[192:195], v[114:117]
	v_mfma_f32_16x16x32_bf16 v[118:121], v[162:165], v[192:195], v[118:121]
	v_mfma_f32_16x16x32_bf16 v[102:105], v[162:165], v[200:203], v[102:105]
	v_mfma_f32_16x16x32_bf16 v[98:101], v[176:179], v[200:203], v[98:101]
	v_mfma_f32_16x16x32_bf16 v[82:85], v[176:179], v[208:211], v[82:85]
	v_mfma_f32_16x16x32_bf16 v[86:89], v[162:165], v[208:211], v[86:89]
	v_mfma_f32_16x16x32_bf16 v[134:137], v[172:175], v[188:191], v[134:137]
	v_mfma_f32_16x16x32_bf16 v[130:133], v[180:183], v[188:191], v[130:133]
	v_mfma_f32_16x16x32_bf16 v[114:117], v[180:183], v[196:199], v[114:117]
	v_mfma_f32_16x16x32_bf16 v[118:121], v[172:175], v[196:199], v[118:121]
	v_mfma_f32_16x16x32_bf16 v[102:105], v[172:175], v[204:207], v[102:105]
	v_mfma_f32_16x16x32_bf16 v[98:101], v[180:183], v[204:207], v[98:101]
	v_mfma_f32_16x16x32_bf16 v[82:85], v[180:183], v[212:215], v[82:85]
	v_mfma_f32_16x16x32_bf16 v[86:89], v[172:175], v[212:215], v[86:89]
	s_setprio 0
	s_barrier
; #define PG8_STAGE(bufoff, gbase, voff) do { _Pragma("unroll") for (int _i = 0; _i < 2; ++_i) \
;         __builtin_amdgcn_global_load_lds((const unsigned*)((const char*)(gbase) + (voff)[_i]), (PG8_LAS unsigned*)(lds + (bufoff) + ldsw + _i * 8192), 16, 0, 0); } while (0)
; #define PG8_LDA(dst, b, h) do { _Pragma("unroll") for (int m = 0; m < 4; ++m) _Pragma("unroll") for (int k = 0; k < 2; ++k) dst[m][k] = *(const PG8_LAS bf16x8*)(lds + PG8_SA(b, h) + aoff + m * 2048 + k * 1024); } while (0)
; #define PG8_MMA(ai, bj, At, Bt) do { __builtin_amdgcn_s_setprio(1); _Pragma("unroll") for (int m = 0; m < 4; ++m) _Pragma("unroll") for (int n = 0; n < 2; ++n) _Pragma("unroll") for (int k = 0; k < 2; ++k) \
;         acc[ai][bj][m][n] = __builtin_amdgcn_mfma_f32_16x16x32_bf16(Bt[n][k], At[m][k], acc[ai][bj][m][n], 0, 0, 0); __builtin_amdgcn_s_setprio(0); } while (0)
; #define PG8_WAIT_V(n) asm volatile("s_waitcnt vmcnt(" #n ")" ::: "memory")
; #define PG8_WAIT_L(n) asm volatile("s_waitcnt lgkmcnt(" #n ")" ::: "memory")
; #define PG8_BAR __builtin_amdgcn_s_barrier()
; #define PG8_SCHED __builtin_amdgcn_sched_barrier(0)
; template <class Epi, class Sched, bool ALIGN_EPI = false, bool SP2 = false>
; __device__ __forceinline__ void gemm_phase(PG8_LAS unsigned char* lds, const Gemm g, const Sched& S, const Epi& E) {
;     ...
;             PG8_LDA(At, 1, 1); PG8_STAGE(PG8_SB(1, 0), b3, voffB); PG8_STAGE(PG8_SB(1, 1), b3 + hstepB, voffB); PG8_STAGE(PG8_SA(1, 0), a3, voffA);
;             PG8_WAIT_V(8); PG8_WAIT_L(0); PG8_BAR; PG8_MMA(1, 0, At, B0); PG8_MMA(1, 1, At, B1); PG8_BAR; PG8_SCHED;
	s_add_i32 s36, s64, s39
	v_lshl_add_u64 v[216:217], v[216:217], 0, s[6:7]
	s_mov_b32 m0, s36
	ds_read_b128 v[184:187], v170 offset:49152
	ds_read_b128 v[188:191], v170 offset:50176
	ds_read_b128 v[192:195], v170 offset:51200
	ds_read_b128 v[196:199], v170 offset:52224
	ds_read_b128 v[200:203], v170 offset:53248
	ds_read_b128 v[204:207], v170 offset:54272
	ds_read_b128 v[208:211], v170 offset:55296
	ds_read_b128 v[212:215], v170 offset:56320
	global_load_lds_dwordx4 v[216:217], off
	s_add_i32 m0, s36, 0x2000
	s_add_u32 s34, s34, 0x100080
	v_lshl_add_u64 v[216:217], v[218:219], 0, s[6:7]
	s_addc_u32 s35, s35, 0
	s_add_i32 s36, s65, s39
	global_load_lds_dwordx4 v[216:217], off
	v_lshl_add_u64 v[216:217], s[34:35], 0, v[148:149]
	s_mov_b32 m0, s36
	s_nop 0
	global_load_lds_dwordx4 v[216:217], off
	v_lshl_add_u64 v[216:217], s[34:35], 0, v[152:153]
	s_add_i32 m0, s36, 0x2000
	s_nop 0
	global_load_lds_dwordx4 v[216:217], off
	v_lshl_add_u64 v[216:217], v[220:221], 0, s[6:7]
	s_mov_b32 m0, s47
	s_nop 0
	global_load_lds_dwordx4 v[216:217], off
	v_lshl_add_u64 v[216:217], v[222:223], 0, s[6:7]
	s_mov_b32 m0, s48
	s_nop 0
	global_load_lds_dwordx4 v[216:217], off
	s_waitcnt vmcnt(8)
	s_waitcnt lgkmcnt(0)
	s_barrier
	s_setprio 1
	s_waitcnt lgkmcnt(0)
	v_mfma_f32_16x16x32_bf16 v[62:65], v[66:69], v[184:187], v[62:65]
	v_mfma_f32_16x16x32_bf16 v[58:61], v[74:77], v[184:187], v[58:61]
	v_mfma_f32_16x16x32_bf16 v[42:45], v[74:77], v[192:195], v[42:45]
	v_mfma_f32_16x16x32_bf16 v[46:49], v[66:69], v[192:195], v[46:49]
	v_mfma_f32_16x16x32_bf16 v[30:33], v[66:69], v[200:203], v[30:33]
	v_mfma_f32_16x16x32_bf16 v[26:29], v[74:77], v[200:203], v[26:29]
	v_mfma_f32_16x16x32_bf16 v[18:21], v[74:77], v[208:211], v[18:21]
	v_mfma_f32_16x16x32_bf16 v[22:25], v[66:69], v[208:211], v[22:25]
	v_mfma_f32_16x16x32_bf16 v[62:65], v[70:73], v[188:191], v[62:65]
	v_mfma_f32_16x16x32_bf16 v[58:61], v[78:81], v[188:191], v[58:61]
	v_mfma_f32_16x16x32_bf16 v[42:45], v[78:81], v[196:199], v[42:45]
	v_mfma_f32_16x16x32_bf16 v[46:49], v[70:73], v[196:199], v[46:49]
	v_mfma_f32_16x16x32_bf16 v[30:33], v[70:73], v[204:207], v[30:33]
	v_mfma_f32_16x16x32_bf16 v[26:29], v[78:81], v[204:207], v[26:29]
	v_mfma_f32_16x16x32_bf16 v[18:21], v[78:81], v[212:215], v[18:21]
	v_mfma_f32_16x16x32_bf16 v[22:25], v[70:73], v[212:215], v[22:25]
	s_setprio 0
	s_setprio 1
	v_mfma_f32_16x16x32_bf16 v[54:57], v[162:165], v[184:187], v[54:57]
	v_mfma_f32_16x16x32_bf16 v[50:53], v[176:179], v[184:187], v[50:53]
	v_mfma_f32_16x16x32_bf16 v[34:37], v[176:179], v[192:195], v[34:37]
	v_mfma_f32_16x16x32_bf16 v[38:41], v[162:165], v[192:195], v[38:41]
	v_mfma_f32_16x16x32_bf16 v[14:17], v[162:165], v[200:203], v[14:17]
	v_mfma_f32_16x16x32_bf16 v[10:13], v[176:179], v[200:203], v[10:13]
	v_mfma_f32_16x16x32_bf16 v[2:5], v[176:179], v[208:211], v[2:5]
	v_mfma_f32_16x16x32_bf16 v[6:9], v[162:165], v[208:211], v[6:9]
	v_mfma_f32_16x16x32_bf16 v[54:57], v[172:175], v[188:191], v[54:57]
	v_mfma_f32_16x16x32_bf16 v[50:53], v[180:183], v[188:191], v[50:53]
	v_mfma_f32_16x16x32_bf16 v[34:37], v[180:183], v[196:199], v[34:37]
	v_mfma_f32_16x16x32_bf16 v[38:41], v[172:175], v[196:199], v[38:41]
	v_mfma_f32_16x16x32_bf16 v[14:17], v[172:175], v[204:207], v[14:17]
	v_mfma_f32_16x16x32_bf16 v[10:13], v[180:183], v[204:207], v[10:13]
	v_mfma_f32_16x16x32_bf16 v[2:5], v[180:183], v[212:215], v[2:5]
	v_mfma_f32_16x16x32_bf16 v[6:9], v[172:175], v[212:215], v[6:9]
	s_setprio 0
	s_barrier
	s_add_i32 s63, s63, 2
	s_add_u32 s30, s30, 0x100
	s_addc_u32 s31, s31, 0
	s_add_u32 s61, s61, 0x100
	s_addc_u32 s62, s62, 0
	s_cmp_gt_u32 s63, 61
	s_cbranch_scc0 .LBB0_1759
	s_and_b64 vcc, exec, s[8:9]
	s_cbranch_vccz .LBB0_1762
	s_barrier

; #define PG8_STAGE(bufoff, gbase, voff) do { _Pragma("unroll") for (int _i = 0; _i < 2; ++_i) \
;         __builtin_amdgcn_global_load_lds((const unsigned*)((const char*)(gbase) + (voff)[_i]), (PG8_LAS unsigned*)(lds + (bufoff) + ldsw + _i * 8192), 16, 0, 0); } while (0)
; #define PG8_LDA(dst, b, h) do { _Pragma("unroll") for (int m = 0; m < 4; ++m) _Pragma("unroll") for (int k = 0; k < 2; ++k) dst[m][k] = *(const PG8_LAS bf16x8*)(lds + PG8_SA(b, h) + aoff + m * 2048 + k * 1024); } while (0)
; #define PG8_LDB(dst, b, h) do { _Pragma("unroll") for (int n = 0; n < 2; ++n) _Pragma("unroll") for (int k = 0; k < 2; ++k) dst[n][k] = *(const PG8_LAS bf16x8*)(lds + PG8_SB(b, h) + boff + n * 2048 + k * 1024); } while (0)
; #define PG8_MMA(ai, bj, At, Bt) do { __builtin_amdgcn_s_setprio(1); _Pragma("unroll") for (int m = 0; m < 4; ++m) _Pragma("unroll") for (int n = 0; n < 2; ++n) _Pragma("unroll") for (int k = 0; k < 2; ++k) \
;         acc[ai][bj][m][n] = __builtin_amdgcn_mfma_f32_16x16x32_bf16(Bt[n][k], At[m][k], acc[ai][bj][m][n], 0, 0, 0); __builtin_amdgcn_s_setprio(0); } while (0)
; #define PG8_WAIT_V(n) asm volatile("s_waitcnt vmcnt(" #n ")" ::: "memory")
; #define PG8_WAIT_L(n) asm volatile("s_waitcnt lgkmcnt(" #n ")" ::: "memory")
; #define PG8_BAR __builtin_amdgcn_s_barrier()
; #define PG8_SCHED __builtin_amdgcn_sched_barrier(0)
; template <class Epi, class Sched, bool ALIGN_EPI = false, bool SP2 = false>
; __device__ __forceinline__ void gemm_phase(PG8_LAS unsigned char* lds, const Gemm g, const Sched& S, const Epi& E) {
;     ...
;             PG8_LDB(B0, 0, 0); PG8_LDB(B1, 0, 1); PG8_SCHED; PG8_LDA(At, 0, 0); PG8_STAGE(PG8_SA(1, 1), a1 + hstep, voffA);
;             PG8_WAIT_V(8); PG8_WAIT_L(0); PG8_BAR; PG8_MMA(0, 0, At, B0); PG8_MMA(0, 1, At, B1); PG8_BAR; PG8_SCHED;
;             PG8_LDA(At, 0, 1); PG8_STAGE(PG8_SB(0, 0), b2, voffB); PG8_STAGE(PG8_SB(0, 1), b2 + hstepB, voffB); PG8_STAGE(PG8_SA(0, 0), a2, voffA);
;             PG8_WAIT_V(8); PG8_WAIT_L(0); PG8_BAR; PG8_MMA(1, 0, At, B0); PG8_MMA(1, 1, At, B1); PG8_BAR; PG8_SCHED;
.LBB0_1889:
	ds_read_b128 v[146:149], v152
	ds_read_b128 v[156:159], v152 offset:1024
	ds_read_b128 v[160:163], v152 offset:2048
	ds_read_b128 v[164:167], v152 offset:3072
	ds_read_b128 v[168:171], v153
	ds_read_b128 v[172:175], v153 offset:1024
	ds_read_b128 v[176:179], v153 offset:2048
	ds_read_b128 v[180:183], v153 offset:3072
	s_add_u32 s16, s14, 0x100
	s_addc_u32 s17, s15, 0
	s_cmp_eq_u32 s44, 60
	s_cselect_b32 s21, s5, s17
	s_cselect_b32 s20, s4, s16
	s_cselect_b32 s19, s13, s43
	s_cselect_b32 s18, s12, s42
	v_lshl_add_u64 v[216:217], s[14:15], 0, v[138:139]
	s_add_i32 m0, s26, 0xc000
	ds_read_b128 v[184:187], v154
	ds_read_b128 v[188:191], v154 offset:1024
	ds_read_b128 v[192:195], v154 offset:2048
	ds_read_b128 v[196:199], v154 offset:3072
	ds_read_b128 v[200:203], v154 offset:4096
	ds_read_b128 v[204:207], v154 offset:5120
	ds_read_b128 v[208:211], v154 offset:6144
	ds_read_b128 v[212:215], v154 offset:7168
	global_load_lds_dwordx4 v[216:217], off
	v_lshl_add_u64 v[216:217], s[14:15], 0, v[140:141]
	s_add_i32 m0, s26, 0xe000
	s_nop 0
	global_load_lds_dwordx4 v[216:217], off
	s_waitcnt vmcnt(8)
	s_waitcnt lgkmcnt(0)
	s_barrier
	s_setprio 1
	s_waitcnt lgkmcnt(0)
	v_mfma_f32_16x16x32_bf16 v[126:129], v[146:149], v[184:187], v[126:129]
	v_mfma_f32_16x16x32_bf16 v[122:125], v[160:163], v[184:187], v[122:125]
	v_mfma_f32_16x16x32_bf16 v[106:109], v[160:163], v[192:195], v[106:109]
	v_mfma_f32_16x16x32_bf16 v[110:113], v[146:149], v[192:195], v[110:113]
	v_mfma_f32_16x16x32_bf16 v[94:97], v[146:149], v[200:203], v[94:97]
	v_mfma_f32_16x16x32_bf16 v[90:93], v[160:163], v[200:203], v[90:93]
	v_mfma_f32_16x16x32_bf16 v[74:77], v[160:163], v[208:211], v[74:77]
	v_mfma_f32_16x16x32_bf16 v[78:81], v[146:149], v[208:211], v[78:81]
	v_mfma_f32_16x16x32_bf16 v[126:129], v[156:159], v[188:191], v[126:129]
	v_mfma_f32_16x16x32_bf16 v[122:125], v[164:167], v[188:191], v[122:125]
	v_mfma_f32_16x16x32_bf16 v[106:109], v[164:167], v[196:199], v[106:109]
	v_mfma_f32_16x16x32_bf16 v[110:113], v[156:159], v[196:199], v[110:113]
	v_mfma_f32_16x16x32_bf16 v[94:97], v[156:159], v[204:207], v[94:97]
	v_mfma_f32_16x16x32_bf16 v[90:93], v[164:167], v[204:207], v[90:93]
	v_mfma_f32_16x16x32_bf16 v[74:77], v[164:167], v[212:215], v[74:77]
	v_mfma_f32_16x16x32_bf16 v[78:81], v[156:159], v[212:215], v[78:81]
	s_setprio 0
	s_setprio 1
	v_mfma_f32_16x16x32_bf16 v[118:121], v[168:171], v[184:187], v[118:121]
	v_mfma_f32_16x16x32_bf16 v[114:117], v[176:179], v[184:187], v[114:117]
	v_mfma_f32_16x16x32_bf16 v[98:101], v[176:179], v[192:195], v[98:101]
	v_mfma_f32_16x16x32_bf16 v[102:105], v[168:171], v[192:195], v[102:105]
	v_mfma_f32_16x16x32_bf16 v[86:89], v[168:171], v[200:203], v[86:89]
	v_mfma_f32_16x16x32_bf16 v[82:85], v[176:179], v[200:203], v[82:85]
	v_mfma_f32_16x16x32_bf16 v[66:69], v[176:179], v[208:211], v[66:69]
	v_mfma_f32_16x16x32_bf16 v[70:73], v[168:171], v[208:211], v[70:73]
	v_mfma_f32_16x16x32_bf16 v[118:121], v[172:175], v[188:191], v[118:121]
	v_mfma_f32_16x16x32_bf16 v[114:117], v[180:183], v[188:191], v[114:117]
	v_mfma_f32_16x16x32_bf16 v[98:101], v[180:183], v[196:199], v[98:101]
	v_mfma_f32_16x16x32_bf16 v[102:105], v[172:175], v[196:199], v[102:105]
	v_mfma_f32_16x16x32_bf16 v[86:89], v[172:175], v[204:207], v[86:89]
	v_mfma_f32_16x16x32_bf16 v[82:85], v[180:183], v[204:207], v[82:85]
	v_mfma_f32_16x16x32_bf16 v[66:69], v[180:183], v[212:215], v[66:69]
	v_mfma_f32_16x16x32_bf16 v[70:73], v[172:175], v[212:215], v[70:73]
	s_setprio 0
	s_barrier
	s_add_i32 s14, s35, s2
	v_lshl_add_u64 v[216:217], s[18:19], 0, v[134:135]
	s_mov_b32 m0, s14
	ds_read_b128 v[184:187], v154 offset:16384
	ds_read_b128 v[188:191], v154 offset:17408
	ds_read_b128 v[192:195], v154 offset:18432
	ds_read_b128 v[196:199], v154 offset:19456
	ds_read_b128 v[200:203], v154 offset:20480
	ds_read_b128 v[204:207], v154 offset:21504
	ds_read_b128 v[208:211], v154 offset:22528
	ds_read_b128 v[212:215], v154 offset:23552
	global_load_lds_dwordx4 v[216:217], off
	s_add_i32 m0, s14, 0x2000
	s_add_u32 s14, s18, 0x108000
	v_lshl_add_u64 v[218:219], s[18:19], 0, v[130:131]
	s_addc_u32 s15, s19, 0
	s_add_i32 s45, s36, s2
	global_load_lds_dwordx4 v[218:219], off
	v_lshl_add_u64 v[220:221], s[14:15], 0, v[134:135]
	s_mov_b32 m0, s45
	v_lshl_add_u64 v[222:223], s[20:21], 0, v[132:133]
	global_load_lds_dwordx4 v[220:221], off
	v_lshl_add_u64 v[220:221], s[14:15], 0, v[130:131]
	s_add_i32 m0, s45, 0x2000
	s_nop 0
	global_load_lds_dwordx4 v[220:221], off
	v_lshl_add_u64 v[220:221], s[20:21], 0, v[136:137]
	s_mov_b32 m0, s26
	s_nop 0
	global_load_lds_dwordx4 v[220:221], off
	s_mov_b32 m0, s27
	s_nop 0
	global_load_lds_dwordx4 v[222:223], off
	s_waitcnt vmcnt(8)
	s_waitcnt lgkmcnt(0)
	s_barrier
; #define PG8_STAGE(bufoff, gbase, voff) do { _Pragma("unroll") for (int _i = 0; _i < 2; ++_i) \
;         __builtin_amdgcn_global_load_lds((const unsigned*)((const char*)(gbase) + (voff)[_i]), (PG8_LAS unsigned*)(lds + (bufoff) + ldsw + _i * 8192), 16, 0, 0); } while (0)
; #define PG8_LDA(dst, b, h) do { _Pragma("unroll") for (int m = 0; m < 4; ++m) _Pragma("unroll") for (int k = 0; k < 2; ++k) dst[m][k] = *(const PG8_LAS bf16x8*)(lds + PG8_SA(b, h) + aoff + m * 2048 + k * 1024); } while (0)
; #define PG8_LDB(dst, b, h) do { _Pragma("unroll") for (int n = 0; n < 2; ++n) _Pragma("unroll") for (int k = 0; k < 2; ++k) dst[n][k] = *(const PG8_LAS bf16x8*)(lds + PG8_SB(b, h) + boff + n * 2048 + k * 1024); } while (0)
; #define PG8_MMA(ai, bj, At, Bt) do { __builtin_amdgcn_s_setprio(1); _Pragma("unroll") for (int m = 0; m < 4; ++m) _Pragma("unroll") for (int n = 0; n < 2; ++n) _Pragma("unroll") for (int k = 0; k < 2; ++k) \
;         acc[ai][bj][m][n] = __builtin_amdgcn_mfma_f32_16x16x32_bf16(Bt[n][k], At[m][k], acc[ai][bj][m][n], 0, 0, 0); __builtin_amdgcn_s_setprio(0); } while (0)
; #define PG8_WAIT_V(n) asm volatile("s_waitcnt vmcnt(" #n ")" ::: "memory")
; #define PG8_WAIT_L(n) asm volatile("s_waitcnt lgkmcnt(" #n ")" ::: "memory")
; #define PG8_BAR __builtin_amdgcn_s_barrier()
; #define PG8_SCHED __builtin_amdgcn_sched_barrier(0)
; template <class Epi, class Sched, bool ALIGN_EPI = false, bool SP2 = false>
; __device__ __forceinline__ void gemm_phase(PG8_LAS unsigned char* lds, const Gemm g, const Sched& S, const Epi& E) {
;     ...
;             PG8_WAIT_V(8); PG8_WAIT_L(0); PG8_BAR; PG8_MMA(1, 0, At, B0); PG8_MMA(1, 1, At, B1); PG8_BAR; PG8_SCHED;
;             PG8_LDB(B0, 1, 0); PG8_LDB(B1, 1, 1); PG8_SCHED; PG8_LDA(At, 1, 0); PG8_STAGE(PG8_SA(0, 1), a2 + hstep, voffA);
;             PG8_WAIT_V(8); PG8_WAIT_L(0); PG8_BAR; PG8_MMA(0, 0, At, B0); PG8_MMA(0, 1, At, B1); PG8_BAR; PG8_SCHED;
	s_setprio 1
	s_waitcnt lgkmcnt(0)
	v_mfma_f32_16x16x32_bf16 v[62:65], v[146:149], v[184:187], v[62:65]
	v_mfma_f32_16x16x32_bf16 v[58:61], v[160:163], v[184:187], v[58:61]
	v_mfma_f32_16x16x32_bf16 v[42:45], v[160:163], v[192:195], v[42:45]
	v_mfma_f32_16x16x32_bf16 v[46:49], v[146:149], v[192:195], v[46:49]
	v_mfma_f32_16x16x32_bf16 v[30:33], v[146:149], v[200:203], v[30:33]
	v_mfma_f32_16x16x32_bf16 v[26:29], v[160:163], v[200:203], v[26:29]
	v_mfma_f32_16x16x32_bf16 v[10:13], v[160:163], v[208:211], v[10:13]
	v_mfma_f32_16x16x32_bf16 v[14:17], v[146:149], v[208:211], v[14:17]
	v_mfma_f32_16x16x32_bf16 v[62:65], v[156:159], v[188:191], v[62:65]
	v_mfma_f32_16x16x32_bf16 v[58:61], v[164:167], v[188:191], v[58:61]
	v_mfma_f32_16x16x32_bf16 v[42:45], v[164:167], v[196:199], v[42:45]
	v_mfma_f32_16x16x32_bf16 v[46:49], v[156:159], v[196:199], v[46:49]
	v_mfma_f32_16x16x32_bf16 v[30:33], v[156:159], v[204:207], v[30:33]
	v_mfma_f32_16x16x32_bf16 v[26:29], v[164:167], v[204:207], v[26:29]
	v_mfma_f32_16x16x32_bf16 v[10:13], v[164:167], v[212:215], v[10:13]
	v_mfma_f32_16x16x32_bf16 v[14:17], v[156:159], v[212:215], v[14:17]
	s_setprio 0
	s_setprio 1
	v_mfma_f32_16x16x32_bf16 v[54:57], v[168:171], v[184:187], v[54:57]
	v_mfma_f32_16x16x32_bf16 v[50:53], v[176:179], v[184:187], v[50:53]
	v_mfma_f32_16x16x32_bf16 v[34:37], v[176:179], v[192:195], v[34:37]
	v_mfma_f32_16x16x32_bf16 v[38:41], v[168:171], v[192:195], v[38:41]
	v_mfma_f32_16x16x32_bf16 v[22:25], v[168:171], v[200:203], v[22:25]
	v_mfma_f32_16x16x32_bf16 v[18:21], v[176:179], v[200:203], v[18:21]
	v_mfma_f32_16x16x32_bf16 v[2:5], v[176:179], v[208:211], v[2:5]
	v_mfma_f32_16x16x32_bf16 v[6:9], v[168:171], v[208:211], v[6:9]
	v_mfma_f32_16x16x32_bf16 v[54:57], v[172:175], v[188:191], v[54:57]
	v_mfma_f32_16x16x32_bf16 v[50:53], v[180:183], v[188:191], v[50:53]
	v_mfma_f32_16x16x32_bf16 v[34:37], v[180:183], v[196:199], v[34:37]
	v_mfma_f32_16x16x32_bf16 v[38:41], v[172:175], v[196:199], v[38:41]
	v_mfma_f32_16x16x32_bf16 v[22:25], v[172:175], v[204:207], v[22:25]
	v_mfma_f32_16x16x32_bf16 v[18:21], v[180:183], v[204:207], v[18:21]
	v_mfma_f32_16x16x32_bf16 v[2:5], v[180:183], v[212:215], v[2:5]
	v_mfma_f32_16x16x32_bf16 v[6:9], v[172:175], v[212:215], v[6:9]
	s_setprio 0
	s_barrier
	s_add_i32 s45, 0, 0x18000
	v_add_u32_e32 v155, s45, v150
	s_add_i32 s46, 0, 0x1c000
	ds_read_b128 v[146:149], v155
	ds_read_b128 v[156:159], v155 offset:1024
	ds_read_b128 v[160:163], v155 offset:2048
	ds_read_b128 v[164:167], v155 offset:3072
	v_add_u32_e32 v155, s46, v150
	ds_read_b128 v[168:171], v155
	ds_read_b128 v[172:175], v155 offset:1024
	ds_read_b128 v[176:179], v155 offset:2048
	ds_read_b128 v[180:183], v155 offset:3072
	s_add_u32 s14, s20, 0x108000
	s_addc_u32 s15, s21, 0
	s_mov_b32 m0, s28
	v_lshl_add_u64 v[224:225], s[14:15], 0, v[136:137]
	ds_read_b128 v[184:187], v154 offset:32768
	ds_read_b128 v[188:191], v154 offset:33792
	ds_read_b128 v[192:195], v154 offset:34816
	ds_read_b128 v[196:199], v154 offset:35840
	ds_read_b128 v[200:203], v154 offset:36864
	ds_read_b128 v[204:207], v154 offset:37888
	ds_read_b128 v[208:211], v154 offset:38912
	ds_read_b128 v[212:215], v154 offset:39936
	global_load_lds_dwordx4 v[224:225], off
	v_lshl_add_u64 v[224:225], s[14:15], 0, v[132:133]
	s_mov_b32 m0, s29
	s_nop 0
	global_load_lds_dwordx4 v[224:225], off
	s_waitcnt vmcnt(8)
	s_waitcnt lgkmcnt(0)
	s_barrier
	s_setprio 1
	s_waitcnt lgkmcnt(0)
	v_mfma_f32_16x16x32_bf16 v[126:129], v[146:149], v[184:187], v[126:129]
	v_mfma_f32_16x16x32_bf16 v[122:125], v[160:163], v[184:187], v[122:125]
	v_mfma_f32_16x16x32_bf16 v[106:109], v[160:163], v[192:195], v[106:109]
	v_mfma_f32_16x16x32_bf16 v[110:113], v[146:149], v[192:195], v[110:113]
	v_mfma_f32_16x16x32_bf16 v[94:97], v[146:149], v[200:203], v[94:97]
	v_mfma_f32_16x16x32_bf16 v[90:93], v[160:163], v[200:203], v[90:93]
	v_mfma_f32_16x16x32_bf16 v[74:77], v[160:163], v[208:211], v[74:77]
	v_mfma_f32_16x16x32_bf16 v[78:81], v[146:149], v[208:211], v[78:81]
	v_mfma_f32_16x16x32_bf16 v[126:129], v[156:159], v[188:191], v[126:129]
	v_mfma_f32_16x16x32_bf16 v[122:125], v[164:167], v[188:191], v[122:125]
	v_mfma_f32_16x16x32_bf16 v[106:109], v[164:167], v[196:199], v[106:109]
	v_mfma_f32_16x16x32_bf16 v[110:113], v[156:159], v[196:199], v[110:113]
	v_mfma_f32_16x16x32_bf16 v[94:97], v[156:159], v[204:207], v[94:97]
	v_mfma_f32_16x16x32_bf16 v[90:93], v[164:167], v[204:207], v[90:93]
	v_mfma_f32_16x16x32_bf16 v[74:77], v[164:167], v[212:215], v[74:77]
	v_mfma_f32_16x16x32_bf16 v[78:81], v[156:159], v[212:215], v[78:81]
	s_setprio 0
	s_setprio 1
	v_mfma_f32_16x16x32_bf16 v[118:121], v[168:171], v[184:187], v[118:121]
	v_mfma_f32_16x16x32_bf16 v[114:117], v[176:179], v[184:187], v[114:117]
	v_mfma_f32_16x16x32_bf16 v[98:101], v[176:179], v[192:195], v[98:101]
	v_mfma_f32_16x16x32_bf16 v[102:105], v[168:171], v[192:195], v[102:105]
	v_mfma_f32_16x16x32_bf16 v[86:89], v[168:171], v[200:203], v[86:89]
	v_mfma_f32_16x16x32_bf16 v[82:85], v[176:179], v[200:203], v[82:85]
	v_mfma_f32_16x16x32_bf16 v[66:69], v[176:179], v[208:211], v[66:69]
	v_mfma_f32_16x16x32_bf16 v[70:73], v[168:171], v[208:211], v[70:73]
	v_mfma_f32_16x16x32_bf16 v[118:121], v[172:175], v[188:191], v[118:121]
	v_mfma_f32_16x16x32_bf16 v[114:117], v[180:183], v[188:191], v[114:117]
	v_mfma_f32_16x16x32_bf16 v[98:101], v[180:183], v[196:199], v[98:101]
	v_mfma_f32_16x16x32_bf16 v[102:105], v[172:175], v[196:199], v[102:105]
	v_mfma_f32_16x16x32_bf16 v[86:89], v[172:175], v[204:207], v[86:89]
	v_mfma_f32_16x16x32_bf16 v[82:85], v[180:183], v[204:207], v[82:85]
	v_mfma_f32_16x16x32_bf16 v[66:69], v[180:183], v[212:215], v[66:69]
	v_mfma_f32_16x16x32_bf16 v[70:73], v[172:175], v[212:215], v[70:73]
	s_setprio 0
	s_barrier
; #define PG8_STAGE(bufoff, gbase, voff) do { _Pragma("unroll") for (int _i = 0; _i < 2; ++_i) \
;         __builtin_amdgcn_global_load_lds((const unsigned*)((const char*)(gbase) + (voff)[_i]), (PG8_LAS unsigned*)(lds + (bufoff) + ldsw + _i * 8192), 16, 0, 0); } while (0)
; #define PG8_LDA(dst, b, h) do { _Pragma("unroll") for (int m = 0; m < 4; ++m) _Pragma("unroll") for (int k = 0; k < 2; ++k) dst[m][k] = *(const PG8_LAS bf16x8*)(lds + PG8_SA(b, h) + aoff + m * 2048 + k * 1024); } while (0)
; #define PG8_MMA(ai, bj, At, Bt) do { __builtin_amdgcn_s_setprio(1); _Pragma("unroll") for (int m = 0; m < 4; ++m) _Pragma("unroll") for (int n = 0; n < 2; ++n) _Pragma("unroll") for (int k = 0; k < 2; ++k) \
;         acc[ai][bj][m][n] = __builtin_amdgcn_mfma_f32_16x16x32_bf16(Bt[n][k], At[m][k], acc[ai][bj][m][n], 0, 0, 0); __builtin_amdgcn_s_setprio(0); } while (0)
; #define PG8_WAIT_V(n) asm volatile("s_waitcnt vmcnt(" #n ")" ::: "memory")
; #define PG8_WAIT_L(n) asm volatile("s_waitcnt lgkmcnt(" #n ")" ::: "memory")
; #define PG8_BAR __builtin_amdgcn_s_barrier()
; #define PG8_SCHED __builtin_amdgcn_sched_barrier(0)
; template <class Epi, class Sched, bool ALIGN_EPI = false, bool SP2 = false>
; __device__ __forceinline__ void gemm_phase(PG8_LAS unsigned char* lds, const Gemm g, const Sched& S, const Epi& E) {
;     ...
;             PG8_LDA(At, 1, 1); PG8_STAGE(PG8_SB(1, 0), b3, voffB); PG8_STAGE(PG8_SB(1, 1), b3 + hstepB, voffB); PG8_STAGE(PG8_SA(1, 0), a3, voffA);
;             PG8_WAIT_V(8); PG8_WAIT_L(0); PG8_BAR; PG8_MMA(1, 0, At, B0); PG8_MMA(1, 1, At, B1); PG8_BAR; PG8_SCHED;
	s_add_i32 s14, s45, s2
	v_lshl_add_u64 v[216:217], v[216:217], 0, s[8:9]
	s_mov_b32 m0, s14
	ds_read_b128 v[184:187], v154 offset:49152
	ds_read_b128 v[188:191], v154 offset:50176
	ds_read_b128 v[192:195], v154 offset:51200
	ds_read_b128 v[196:199], v154 offset:52224
	ds_read_b128 v[200:203], v154 offset:53248
	ds_read_b128 v[204:207], v154 offset:54272
	ds_read_b128 v[208:211], v154 offset:55296
	ds_read_b128 v[212:215], v154 offset:56320
	global_load_lds_dwordx4 v[216:217], off
	s_add_i32 m0, s14, 0x2000
	s_add_u32 s14, s18, 0x108080
	v_lshl_add_u64 v[216:217], v[218:219], 0, s[8:9]
	s_addc_u32 s15, s19, 0
	s_add_i32 s18, s46, s2
	global_load_lds_dwordx4 v[216:217], off
	v_lshl_add_u64 v[216:217], s[14:15], 0, v[134:135]
	s_mov_b32 m0, s18
	s_nop 0
	global_load_lds_dwordx4 v[216:217], off
	v_lshl_add_u64 v[216:217], s[14:15], 0, v[130:131]
	s_add_i32 m0, s18, 0x2000
	s_nop 0
	global_load_lds_dwordx4 v[216:217], off
	v_lshl_add_u64 v[216:217], v[220:221], 0, s[8:9]
	s_mov_b32 m0, s31
	s_nop 0
	global_load_lds_dwordx4 v[216:217], off
	v_lshl_add_u64 v[216:217], v[222:223], 0, s[8:9]
	s_mov_b32 m0, s33
	s_nop 0
	global_load_lds_dwordx4 v[216:217], off
	s_waitcnt vmcnt(8)
	s_waitcnt lgkmcnt(0)
	s_barrier
	s_setprio 1
	s_waitcnt lgkmcnt(0)
	v_mfma_f32_16x16x32_bf16 v[62:65], v[146:149], v[184:187], v[62:65]
	v_mfma_f32_16x16x32_bf16 v[58:61], v[160:163], v[184:187], v[58:61]
	v_mfma_f32_16x16x32_bf16 v[42:45], v[160:163], v[192:195], v[42:45]
	v_mfma_f32_16x16x32_bf16 v[46:49], v[146:149], v[192:195], v[46:49]
	v_mfma_f32_16x16x32_bf16 v[30:33], v[146:149], v[200:203], v[30:33]
	v_mfma_f32_16x16x32_bf16 v[26:29], v[160:163], v[200:203], v[26:29]
	v_mfma_f32_16x16x32_bf16 v[10:13], v[160:163], v[208:211], v[10:13]
	v_mfma_f32_16x16x32_bf16 v[14:17], v[146:149], v[208:211], v[14:17]
	v_mfma_f32_16x16x32_bf16 v[62:65], v[156:159], v[188:191], v[62:65]
	v_mfma_f32_16x16x32_bf16 v[58:61], v[164:167], v[188:191], v[58:61]
	v_mfma_f32_16x16x32_bf16 v[42:45], v[164:167], v[196:199], v[42:45]
	v_mfma_f32_16x16x32_bf16 v[46:49], v[156:159], v[196:199], v[46:49]
	v_mfma_f32_16x16x32_bf16 v[30:33], v[156:159], v[204:207], v[30:33]
	v_mfma_f32_16x16x32_bf16 v[26:29], v[164:167], v[204:207], v[26:29]
	v_mfma_f32_16x16x32_bf16 v[10:13], v[164:167], v[212:215], v[10:13]
	v_mfma_f32_16x16x32_bf16 v[14:17], v[156:159], v[212:215], v[14:17]
	s_setprio 0
	s_setprio 1
	v_mfma_f32_16x16x32_bf16 v[54:57], v[168:171], v[184:187], v[54:57]
	v_mfma_f32_16x16x32_bf16 v[50:53], v[176:179], v[184:187], v[50:53]
	v_mfma_f32_16x16x32_bf16 v[34:37], v[176:179], v[192:195], v[34:37]
	v_mfma_f32_16x16x32_bf16 v[38:41], v[168:171], v[192:195], v[38:41]
	v_mfma_f32_16x16x32_bf16 v[22:25], v[168:171], v[200:203], v[22:25]
	v_mfma_f32_16x16x32_bf16 v[18:21], v[176:179], v[200:203], v[18:21]
	v_mfma_f32_16x16x32_bf16 v[2:5], v[176:179], v[208:211], v[2:5]
	v_mfma_f32_16x16x32_bf16 v[6:9], v[168:171], v[208:211], v[6:9]
	v_mfma_f32_16x16x32_bf16 v[54:57], v[172:175], v[188:191], v[54:57]
	v_mfma_f32_16x16x32_bf16 v[50:53], v[180:183], v[188:191], v[50:53]
	v_mfma_f32_16x16x32_bf16 v[34:37], v[180:183], v[196:199], v[34:37]
	v_mfma_f32_16x16x32_bf16 v[38:41], v[172:175], v[196:199], v[38:41]
	v_mfma_f32_16x16x32_bf16 v[22:25], v[172:175], v[204:207], v[22:25]
	v_mfma_f32_16x16x32_bf16 v[18:21], v[180:183], v[204:207], v[18:21]
	v_mfma_f32_16x16x32_bf16 v[2:5], v[180:183], v[212:215], v[2:5]
	v_mfma_f32_16x16x32_bf16 v[6:9], v[172:175], v[212:215], v[6:9]
	s_setprio 0
	s_barrier
	s_add_i32 s44, s44, 2
	s_add_u32 s42, s42, 0x100
	s_addc_u32 s43, s43, 0
	s_cmp_gt_u32 s44, 61
	s_mov_b64 s[14:15], s[16:17]
	s_cbranch_scc0 .LBB0_1889
	s_and_b64 vcc, exec, s[10:11]
	s_cbranch_vccz .LBB0_1892
	s_barrier

; #define PG8_STAGE(bufoff, gbase, voff) do { _Pragma("unroll") for (int _i = 0; _i < 2; ++_i) \
;         __builtin_amdgcn_global_load_lds((const unsigned*)((const char*)(gbase) + (voff)[_i]), (PG8_LAS unsigned*)(lds + (bufoff) + ldsw + _i * 8192), 16, 0, 0); } while (0)
; #define PG8_LDA(dst, b, h) do { _Pragma("unroll") for (int m = 0; m < 4; ++m) _Pragma("unroll") for (int k = 0; k < 2; ++k) dst[m][k] = *(const PG8_LAS bf16x8*)(lds + PG8_SA(b, h) + aoff + m * 2048 + k * 1024); } while (0)
; #define PG8_LDB(dst, b, h) do { _Pragma("unroll") for (int n = 0; n < 2; ++n) _Pragma("unroll") for (int k = 0; k < 2; ++k) dst[n][k] = *(const PG8_LAS bf16x8*)(lds + PG8_SB(b, h) + boff + n * 2048 + k * 1024); } while (0)
; #define PG8_MMA(ai, bj, At, Bt) do { __builtin_amdgcn_s_setprio(1); _Pragma("unroll") for (int m = 0; m < 4; ++m) _Pragma("unroll") for (int n = 0; n < 2; ++n) _Pragma("unroll") for (int k = 0; k < 2; ++k) \
;         acc[ai][bj][m][n] = __builtin_amdgcn_mfma_f32_16x16x32_bf16(Bt[n][k], At[m][k], acc[ai][bj][m][n], 0, 0, 0); __builtin_amdgcn_s_setprio(0); } while (0)
; #define PG8_WAIT_V(n) asm volatile("s_waitcnt vmcnt(" #n ")" ::: "memory")
; #define PG8_WAIT_L(n) asm volatile("s_waitcnt lgkmcnt(" #n ")" ::: "memory")
; #define PG8_BAR __builtin_amdgcn_s_barrier()
; #define PG8_SCHED __builtin_amdgcn_sched_barrier(0)
; template <class Epi, class Sched, bool ALIGN_EPI = false, bool SP2 = false>
; __device__ __forceinline__ void gemm_phase(PG8_LAS unsigned char* lds, const Gemm g, const Sched& S, const Epi& E) {
;     ...
;             PG8_LDB(B0, 0, 0); PG8_LDB(B1, 0, 1); PG8_SCHED; PG8_LDA(At, 0, 0); PG8_STAGE(PG8_SA(1, 1), a1 + hstep, voffA);
;             PG8_WAIT_V(8); PG8_WAIT_L(0); PG8_BAR; PG8_MMA(0, 0, At, B0); PG8_MMA(0, 1, At, B1); PG8_BAR; PG8_SCHED;
;             PG8_LDA(At, 0, 1); PG8_STAGE(PG8_SB(0, 0), b2, voffB); PG8_STAGE(PG8_SB(0, 1), b2 + hstepB, voffB); PG8_STAGE(PG8_SA(0, 0), a2, voffA);
;             PG8_WAIT_V(8); PG8_WAIT_L(0); PG8_BAR; PG8_MMA(1, 0, At, B0); PG8_MMA(1, 1, At, B1); PG8_BAR; PG8_SCHED;
.LBB0_2165:
	ds_read_b128 v[128:131], v167
	ds_read_b128 v[132:135], v167 offset:1024
	ds_read_b128 v[136:139], v167 offset:2048
	ds_read_b128 v[140:143], v167 offset:3072
	ds_read_b128 v[160:163], v168
	ds_read_b128 v[170:173], v168 offset:1024
	ds_read_b128 v[174:177], v168 offset:2048
	ds_read_b128 v[178:181], v168 offset:3072
	s_add_u32 s16, s14, 0x100
	s_addc_u32 s17, s15, 0
	s_cmpk_eq_i32 s57, 0xa8
	s_cselect_b32 s21, s5, s17
	s_cselect_b32 s20, s4, s16
	s_cselect_b32 s19, s13, s56
	s_cselect_b32 s18, s12, s55
	v_lshl_add_u64 v[214:215], s[14:15], 0, v[152:153]
	s_add_i32 m0, s25, 0xc000
	ds_read_b128 v[182:185], v169
	ds_read_b128 v[186:189], v169 offset:1024
	ds_read_b128 v[190:193], v169 offset:2048
	ds_read_b128 v[194:197], v169 offset:3072
	ds_read_b128 v[198:201], v169 offset:4096
	ds_read_b128 v[202:205], v169 offset:5120
	ds_read_b128 v[206:209], v169 offset:6144
	ds_read_b128 v[210:213], v169 offset:7168
	global_load_lds_dwordx4 v[214:215], off
	v_lshl_add_u64 v[214:215], s[14:15], 0, v[154:155]
	s_add_i32 m0, s25, 0xe000
	s_nop 0
	global_load_lds_dwordx4 v[214:215], off
	s_waitcnt vmcnt(8)
	s_waitcnt lgkmcnt(0)
	s_barrier
	s_setprio 1
	s_waitcnt lgkmcnt(0)
	v_mfma_f32_16x16x32_bf16 v[124:127], v[128:131], v[182:185], v[124:127]
	v_mfma_f32_16x16x32_bf16 v[120:123], v[136:139], v[182:185], v[120:123]
	v_mfma_f32_16x16x32_bf16 v[108:111], v[136:139], v[190:193], v[108:111]
	v_mfma_f32_16x16x32_bf16 v[116:119], v[128:131], v[190:193], v[116:119]
	v_mfma_f32_16x16x32_bf16 v[92:95], v[128:131], v[198:201], v[92:95]
	v_mfma_f32_16x16x32_bf16 v[88:91], v[136:139], v[198:201], v[88:91]
	v_mfma_f32_16x16x32_bf16 v[72:75], v[136:139], v[206:209], v[72:75]
	v_mfma_f32_16x16x32_bf16 v[80:83], v[128:131], v[206:209], v[80:83]
	v_mfma_f32_16x16x32_bf16 v[124:127], v[132:135], v[186:189], v[124:127]
	v_mfma_f32_16x16x32_bf16 v[120:123], v[140:143], v[186:189], v[120:123]
	v_mfma_f32_16x16x32_bf16 v[108:111], v[140:143], v[194:197], v[108:111]
	v_mfma_f32_16x16x32_bf16 v[116:119], v[132:135], v[194:197], v[116:119]
	v_mfma_f32_16x16x32_bf16 v[92:95], v[132:135], v[202:205], v[92:95]
	v_mfma_f32_16x16x32_bf16 v[88:91], v[140:143], v[202:205], v[88:91]
	v_mfma_f32_16x16x32_bf16 v[72:75], v[140:143], v[210:213], v[72:75]
	v_mfma_f32_16x16x32_bf16 v[80:83], v[132:135], v[210:213], v[80:83]
	s_setprio 0
	s_setprio 1
	v_mfma_f32_16x16x32_bf16 v[112:115], v[160:163], v[182:185], v[112:115]
	v_mfma_f32_16x16x32_bf16 v[104:107], v[174:177], v[182:185], v[104:107]
	v_mfma_f32_16x16x32_bf16 v[96:99], v[174:177], v[190:193], v[96:99]
	v_mfma_f32_16x16x32_bf16 v[100:103], v[160:163], v[190:193], v[100:103]
	v_mfma_f32_16x16x32_bf16 v[84:87], v[160:163], v[198:201], v[84:87]
	v_mfma_f32_16x16x32_bf16 v[76:79], v[174:177], v[198:201], v[76:79]
	v_mfma_f32_16x16x32_bf16 v[64:67], v[174:177], v[206:209], v[64:67]
	v_mfma_f32_16x16x32_bf16 v[68:71], v[160:163], v[206:209], v[68:71]
	v_mfma_f32_16x16x32_bf16 v[112:115], v[170:173], v[186:189], v[112:115]
	v_mfma_f32_16x16x32_bf16 v[104:107], v[178:181], v[186:189], v[104:107]
	v_mfma_f32_16x16x32_bf16 v[96:99], v[178:181], v[194:197], v[96:99]
	v_mfma_f32_16x16x32_bf16 v[100:103], v[170:173], v[194:197], v[100:103]
	v_mfma_f32_16x16x32_bf16 v[84:87], v[170:173], v[202:205], v[84:87]
	v_mfma_f32_16x16x32_bf16 v[76:79], v[178:181], v[202:205], v[76:79]
	v_mfma_f32_16x16x32_bf16 v[64:67], v[178:181], v[210:213], v[64:67]
	v_mfma_f32_16x16x32_bf16 v[68:71], v[170:173], v[210:213], v[68:71]
	s_setprio 0
	s_barrier
	s_add_i32 s14, s36, s24
	v_lshl_add_u64 v[214:215], s[18:19], 0, v[146:147]
	s_mov_b32 m0, s14
	ds_read_b128 v[182:185], v169 offset:16384
	ds_read_b128 v[186:189], v169 offset:17408
	ds_read_b128 v[190:193], v169 offset:18432
	ds_read_b128 v[194:197], v169 offset:19456
	ds_read_b128 v[198:201], v169 offset:20480
	ds_read_b128 v[202:205], v169 offset:21504
	ds_read_b128 v[206:209], v169 offset:22528
	ds_read_b128 v[210:213], v169 offset:23552
	global_load_lds_dwordx4 v[214:215], off
	s_add_i32 m0, s14, 0x2000
	s_add_u32 s14, s18, 0x2b0000
	v_lshl_add_u64 v[216:217], s[18:19], 0, v[150:151]
	s_addc_u32 s15, s19, 0
	s_add_i32 s58, s37, s24
	global_load_lds_dwordx4 v[216:217], off
	v_lshl_add_u64 v[218:219], s[14:15], 0, v[146:147]
	s_mov_b32 m0, s58
	v_lshl_add_u64 v[220:221], s[20:21], 0, v[148:149]
	global_load_lds_dwordx4 v[218:219], off
	v_lshl_add_u64 v[218:219], s[14:15], 0, v[150:151]
	s_add_i32 m0, s58, 0x2000
	s_nop 0
	global_load_lds_dwordx4 v[218:219], off
	v_lshl_add_u64 v[218:219], s[20:21], 0, v[144:145]
	s_mov_b32 m0, s25
	s_nop 0
	global_load_lds_dwordx4 v[218:219], off
	s_mov_b32 m0, s26
	s_nop 0
	global_load_lds_dwordx4 v[220:221], off
	s_waitcnt vmcnt(8)
	s_waitcnt lgkmcnt(0)
	s_barrier
; #define PG8_STAGE(bufoff, gbase, voff) do { _Pragma("unroll") for (int _i = 0; _i < 2; ++_i) \
;         __builtin_amdgcn_global_load_lds((const unsigned*)((const char*)(gbase) + (voff)[_i]), (PG8_LAS unsigned*)(lds + (bufoff) + ldsw + _i * 8192), 16, 0, 0); } while (0)
; #define PG8_LDA(dst, b, h) do { _Pragma("unroll") for (int m = 0; m < 4; ++m) _Pragma("unroll") for (int k = 0; k < 2; ++k) dst[m][k] = *(const PG8_LAS bf16x8*)(lds + PG8_SA(b, h) + aoff + m * 2048 + k * 1024); } while (0)
; #define PG8_LDB(dst, b, h) do { _Pragma("unroll") for (int n = 0; n < 2; ++n) _Pragma("unroll") for (int k = 0; k < 2; ++k) dst[n][k] = *(const PG8_LAS bf16x8*)(lds + PG8_SB(b, h) + boff + n * 2048 + k * 1024); } while (0)
; #define PG8_MMA(ai, bj, At, Bt) do { __builtin_amdgcn_s_setprio(1); _Pragma("unroll") for (int m = 0; m < 4; ++m) _Pragma("unroll") for (int n = 0; n < 2; ++n) _Pragma("unroll") for (int k = 0; k < 2; ++k) \
;         acc[ai][bj][m][n] = __builtin_amdgcn_mfma_f32_16x16x32_bf16(Bt[n][k], At[m][k], acc[ai][bj][m][n], 0, 0, 0); __builtin_amdgcn_s_setprio(0); } while (0)
; #define PG8_WAIT_V(n) asm volatile("s_waitcnt vmcnt(" #n ")" ::: "memory")
; #define PG8_WAIT_L(n) asm volatile("s_waitcnt lgkmcnt(" #n ")" ::: "memory")
; #define PG8_BAR __builtin_amdgcn_s_barrier()
; #define PG8_SCHED __builtin_amdgcn_sched_barrier(0)
; template <class Epi, class Sched, bool ALIGN_EPI = false, bool SP2 = false>
; __device__ __forceinline__ void gemm_phase(PG8_LAS unsigned char* lds, const Gemm g, const Sched& S, const Epi& E) {
;     ...
;             PG8_WAIT_V(8); PG8_WAIT_L(0); PG8_BAR; PG8_MMA(1, 0, At, B0); PG8_MMA(1, 1, At, B1); PG8_BAR; PG8_SCHED;
;             PG8_LDB(B0, 1, 0); PG8_LDB(B1, 1, 1); PG8_SCHED; PG8_LDA(At, 1, 0); PG8_STAGE(PG8_SA(0, 1), a2 + hstep, voffA);
;             PG8_WAIT_V(8); PG8_WAIT_L(0); PG8_BAR; PG8_MMA(0, 0, At, B0); PG8_MMA(0, 1, At, B1); PG8_BAR; PG8_SCHED;
	s_setprio 1
	s_waitcnt lgkmcnt(0)
	v_mfma_f32_16x16x32_bf16 v[60:63], v[128:131], v[182:185], v[60:63]
	v_mfma_f32_16x16x32_bf16 v[56:59], v[136:139], v[182:185], v[56:59]
	v_mfma_f32_16x16x32_bf16 v[40:43], v[136:139], v[190:193], v[40:43]
	v_mfma_f32_16x16x32_bf16 v[48:51], v[128:131], v[190:193], v[48:51]
	v_mfma_f32_16x16x32_bf16 v[28:31], v[128:131], v[198:201], v[28:31]
	v_mfma_f32_16x16x32_bf16 v[24:27], v[136:139], v[198:201], v[24:27]
	v_mfma_f32_16x16x32_bf16 v[12:15], v[136:139], v[206:209], v[12:15]
	v_mfma_f32_16x16x32_bf16 v[20:23], v[128:131], v[206:209], v[20:23]
	v_mfma_f32_16x16x32_bf16 v[60:63], v[132:135], v[186:189], v[60:63]
	v_mfma_f32_16x16x32_bf16 v[56:59], v[140:143], v[186:189], v[56:59]
	v_mfma_f32_16x16x32_bf16 v[40:43], v[140:143], v[194:197], v[40:43]
	v_mfma_f32_16x16x32_bf16 v[48:51], v[132:135], v[194:197], v[48:51]
	v_mfma_f32_16x16x32_bf16 v[28:31], v[132:135], v[202:205], v[28:31]
	v_mfma_f32_16x16x32_bf16 v[24:27], v[140:143], v[202:205], v[24:27]
	v_mfma_f32_16x16x32_bf16 v[12:15], v[140:143], v[210:213], v[12:15]
	v_mfma_f32_16x16x32_bf16 v[20:23], v[132:135], v[210:213], v[20:23]
	s_setprio 0
	s_setprio 1
	v_mfma_f32_16x16x32_bf16 v[52:55], v[160:163], v[182:185], v[52:55]
	v_mfma_f32_16x16x32_bf16 v[44:47], v[174:177], v[182:185], v[44:47]
	v_mfma_f32_16x16x32_bf16 v[32:35], v[174:177], v[190:193], v[32:35]
	v_mfma_f32_16x16x32_bf16 v[36:39], v[160:163], v[190:193], v[36:39]
	v_mfma_f32_16x16x32_bf16 v[16:19], v[160:163], v[198:201], v[16:19]
	v_mfma_f32_16x16x32_bf16 v[8:11], v[174:177], v[198:201], v[8:11]
	v_mfma_f32_16x16x32_bf16 v[0:3], v[174:177], v[206:209], v[0:3]
	v_mfma_f32_16x16x32_bf16 v[4:7], v[160:163], v[206:209], v[4:7]
	v_mfma_f32_16x16x32_bf16 v[52:55], v[170:173], v[186:189], v[52:55]
	v_mfma_f32_16x16x32_bf16 v[44:47], v[178:181], v[186:189], v[44:47]
	v_mfma_f32_16x16x32_bf16 v[32:35], v[178:181], v[194:197], v[32:35]
	v_mfma_f32_16x16x32_bf16 v[36:39], v[170:173], v[194:197], v[36:39]
	v_mfma_f32_16x16x32_bf16 v[16:19], v[170:173], v[202:205], v[16:19]
	v_mfma_f32_16x16x32_bf16 v[8:11], v[178:181], v[202:205], v[8:11]
	v_mfma_f32_16x16x32_bf16 v[0:3], v[178:181], v[210:213], v[0:3]
	v_mfma_f32_16x16x32_bf16 v[4:7], v[170:173], v[210:213], v[4:7]
	s_setprio 0
	s_barrier
	s_add_i32 s58, 0, 0x18000
	s_add_i32 s59, 0, 0x1c000
	v_add_u32_e32 v140, s58, v165
	v_add_u32_e32 v178, s59, v165
	ds_read_b128 v[128:131], v140
	ds_read_b128 v[132:135], v140 offset:1024
	ds_read_b128 v[136:139], v140 offset:2048
	ds_read_b128 v[140:143], v140 offset:3072
	ds_read_b128 v[160:163], v178
	ds_read_b128 v[170:173], v178 offset:1024
	ds_read_b128 v[174:177], v178 offset:2048
	ds_read_b128 v[178:181], v178 offset:3072
	s_add_u32 s14, s20, 0x2b0000
	s_addc_u32 s15, s21, 0
	s_mov_b32 m0, s27
	v_lshl_add_u64 v[222:223], s[14:15], 0, v[144:145]
	ds_read_b128 v[182:185], v169 offset:32768
	ds_read_b128 v[186:189], v169 offset:33792
	ds_read_b128 v[190:193], v169 offset:34816
	ds_read_b128 v[194:197], v169 offset:35840
	ds_read_b128 v[198:201], v169 offset:36864
	ds_read_b128 v[202:205], v169 offset:37888
	ds_read_b128 v[206:209], v169 offset:38912
	ds_read_b128 v[210:213], v169 offset:39936
	global_load_lds_dwordx4 v[222:223], off
	v_lshl_add_u64 v[222:223], s[14:15], 0, v[148:149]
	s_mov_b32 m0, s28
	s_nop 0
	global_load_lds_dwordx4 v[222:223], off
	s_waitcnt vmcnt(8)
	s_waitcnt lgkmcnt(0)
	s_barrier
	s_setprio 1
	s_waitcnt lgkmcnt(0)
	v_mfma_f32_16x16x32_bf16 v[124:127], v[128:131], v[182:185], v[124:127]
	v_mfma_f32_16x16x32_bf16 v[120:123], v[136:139], v[182:185], v[120:123]
	v_mfma_f32_16x16x32_bf16 v[108:111], v[136:139], v[190:193], v[108:111]
	v_mfma_f32_16x16x32_bf16 v[116:119], v[128:131], v[190:193], v[116:119]
	v_mfma_f32_16x16x32_bf16 v[92:95], v[128:131], v[198:201], v[92:95]
	v_mfma_f32_16x16x32_bf16 v[88:91], v[136:139], v[198:201], v[88:91]
	v_mfma_f32_16x16x32_bf16 v[72:75], v[136:139], v[206:209], v[72:75]
	v_mfma_f32_16x16x32_bf16 v[80:83], v[128:131], v[206:209], v[80:83]
	v_mfma_f32_16x16x32_bf16 v[124:127], v[132:135], v[186:189], v[124:127]
	v_mfma_f32_16x16x32_bf16 v[120:123], v[140:143], v[186:189], v[120:123]
	v_mfma_f32_16x16x32_bf16 v[108:111], v[140:143], v[194:197], v[108:111]
	v_mfma_f32_16x16x32_bf16 v[116:119], v[132:135], v[194:197], v[116:119]
	v_mfma_f32_16x16x32_bf16 v[92:95], v[132:135], v[202:205], v[92:95]
	v_mfma_f32_16x16x32_bf16 v[88:91], v[140:143], v[202:205], v[88:91]
	v_mfma_f32_16x16x32_bf16 v[72:75], v[140:143], v[210:213], v[72:75]
	v_mfma_f32_16x16x32_bf16 v[80:83], v[132:135], v[210:213], v[80:83]
	s_setprio 0
	s_setprio 1
	v_mfma_f32_16x16x32_bf16 v[112:115], v[160:163], v[182:185], v[112:115]
	v_mfma_f32_16x16x32_bf16 v[104:107], v[174:177], v[182:185], v[104:107]
	v_mfma_f32_16x16x32_bf16 v[96:99], v[174:177], v[190:193], v[96:99]
	v_mfma_f32_16x16x32_bf16 v[100:103], v[160:163], v[190:193], v[100:103]
	v_mfma_f32_16x16x32_bf16 v[84:87], v[160:163], v[198:201], v[84:87]
	v_mfma_f32_16x16x32_bf16 v[76:79], v[174:177], v[198:201], v[76:79]
	v_mfma_f32_16x16x32_bf16 v[64:67], v[174:177], v[206:209], v[64:67]
	v_mfma_f32_16x16x32_bf16 v[68:71], v[160:163], v[206:209], v[68:71]
	v_mfma_f32_16x16x32_bf16 v[112:115], v[170:173], v[186:189], v[112:115]
	v_mfma_f32_16x16x32_bf16 v[104:107], v[178:181], v[186:189], v[104:107]
	v_mfma_f32_16x16x32_bf16 v[96:99], v[178:181], v[194:197], v[96:99]
	v_mfma_f32_16x16x32_bf16 v[100:103], v[170:173], v[194:197], v[100:103]
	v_mfma_f32_16x16x32_bf16 v[84:87], v[170:173], v[202:205], v[84:87]
	v_mfma_f32_16x16x32_bf16 v[76:79], v[178:181], v[202:205], v[76:79]
	v_mfma_f32_16x16x32_bf16 v[64:67], v[178:181], v[210:213], v[64:67]
	v_mfma_f32_16x16x32_bf16 v[68:71], v[170:173], v[210:213], v[68:71]
	s_setprio 0
	s_barrier
; #define PG8_STAGE(bufoff, gbase, voff) do { _Pragma("unroll") for (int _i = 0; _i < 2; ++_i) \
;         __builtin_amdgcn_global_load_lds((const unsigned*)((const char*)(gbase) + (voff)[_i]), (PG8_LAS unsigned*)(lds + (bufoff) + ldsw + _i * 8192), 16, 0, 0); } while (0)
; #define PG8_LDA(dst, b, h) do { _Pragma("unroll") for (int m = 0; m < 4; ++m) _Pragma("unroll") for (int k = 0; k < 2; ++k) dst[m][k] = *(const PG8_LAS bf16x8*)(lds + PG8_SA(b, h) + aoff + m * 2048 + k * 1024); } while (0)
; #define PG8_MMA(ai, bj, At, Bt) do { __builtin_amdgcn_s_setprio(1); _Pragma("unroll") for (int m = 0; m < 4; ++m) _Pragma("unroll") for (int n = 0; n < 2; ++n) _Pragma("unroll") for (int k = 0; k < 2; ++k) \
;         acc[ai][bj][m][n] = __builtin_amdgcn_mfma_f32_16x16x32_bf16(Bt[n][k], At[m][k], acc[ai][bj][m][n], 0, 0, 0); __builtin_amdgcn_s_setprio(0); } while (0)
; #define PG8_WAIT_V(n) asm volatile("s_waitcnt vmcnt(" #n ")" ::: "memory")
; #define PG8_WAIT_L(n) asm volatile("s_waitcnt lgkmcnt(" #n ")" ::: "memory")
; #define PG8_BAR __builtin_amdgcn_s_barrier()
; #define PG8_SCHED __builtin_amdgcn_sched_barrier(0)
; template <class Epi, class Sched, bool ALIGN_EPI = false, bool SP2 = false>
; __device__ __forceinline__ void gemm_phase(PG8_LAS unsigned char* lds, const Gemm g, const Sched& S, const Epi& E) {
;     ...
;             PG8_LDA(At, 1, 1); PG8_STAGE(PG8_SB(1, 0), b3, voffB); PG8_STAGE(PG8_SB(1, 1), b3 + hstepB, voffB); PG8_STAGE(PG8_SA(1, 0), a3, voffA);
;             PG8_WAIT_V(8); PG8_WAIT_L(0); PG8_BAR; PG8_MMA(1, 0, At, B0); PG8_MMA(1, 1, At, B1); PG8_BAR; PG8_SCHED;
	s_add_i32 s14, s58, s24
	v_lshl_add_u64 v[214:215], v[214:215], 0, s[8:9]
	s_mov_b32 m0, s14
	ds_read_b128 v[182:185], v169 offset:49152
	ds_read_b128 v[186:189], v169 offset:50176
	ds_read_b128 v[190:193], v169 offset:51200
	ds_read_b128 v[194:197], v169 offset:52224
	ds_read_b128 v[198:201], v169 offset:53248
	ds_read_b128 v[202:205], v169 offset:54272
	ds_read_b128 v[206:209], v169 offset:55296
	ds_read_b128 v[210:213], v169 offset:56320
	global_load_lds_dwordx4 v[214:215], off
	s_add_i32 m0, s14, 0x2000
	s_add_u32 s14, s18, 0x2b0080
	v_lshl_add_u64 v[214:215], v[216:217], 0, s[8:9]
	s_addc_u32 s15, s19, 0
	s_add_i32 s18, s59, s24
	global_load_lds_dwordx4 v[214:215], off
	v_lshl_add_u64 v[214:215], s[14:15], 0, v[146:147]
	s_mov_b32 m0, s18
	s_nop 0
	global_load_lds_dwordx4 v[214:215], off
	v_lshl_add_u64 v[214:215], s[14:15], 0, v[150:151]
	s_add_i32 m0, s18, 0x2000
	s_nop 0
	global_load_lds_dwordx4 v[214:215], off
	v_lshl_add_u64 v[214:215], v[218:219], 0, s[8:9]
	s_mov_b32 m0, s33
	s_nop 0
	global_load_lds_dwordx4 v[214:215], off
	v_lshl_add_u64 v[214:215], v[220:221], 0, s[8:9]
	s_mov_b32 m0, s34
	s_nop 0
	global_load_lds_dwordx4 v[214:215], off
	s_waitcnt vmcnt(8)
	s_waitcnt lgkmcnt(0)
	s_barrier
	s_setprio 1
	s_waitcnt lgkmcnt(0)
	v_mfma_f32_16x16x32_bf16 v[60:63], v[128:131], v[182:185], v[60:63]
	v_mfma_f32_16x16x32_bf16 v[56:59], v[136:139], v[182:185], v[56:59]
	v_mfma_f32_16x16x32_bf16 v[40:43], v[136:139], v[190:193], v[40:43]
	v_mfma_f32_16x16x32_bf16 v[48:51], v[128:131], v[190:193], v[48:51]
	v_mfma_f32_16x16x32_bf16 v[28:31], v[128:131], v[198:201], v[28:31]
	v_mfma_f32_16x16x32_bf16 v[24:27], v[136:139], v[198:201], v[24:27]
	v_mfma_f32_16x16x32_bf16 v[12:15], v[136:139], v[206:209], v[12:15]
	v_mfma_f32_16x16x32_bf16 v[20:23], v[128:131], v[206:209], v[20:23]
	v_mfma_f32_16x16x32_bf16 v[60:63], v[132:135], v[186:189], v[60:63]
	v_mfma_f32_16x16x32_bf16 v[56:59], v[140:143], v[186:189], v[56:59]
	v_mfma_f32_16x16x32_bf16 v[40:43], v[140:143], v[194:197], v[40:43]
	v_mfma_f32_16x16x32_bf16 v[48:51], v[132:135], v[194:197], v[48:51]
	v_mfma_f32_16x16x32_bf16 v[28:31], v[132:135], v[202:205], v[28:31]
	v_mfma_f32_16x16x32_bf16 v[24:27], v[140:143], v[202:205], v[24:27]
	v_mfma_f32_16x16x32_bf16 v[12:15], v[140:143], v[210:213], v[12:15]
	v_mfma_f32_16x16x32_bf16 v[20:23], v[132:135], v[210:213], v[20:23]
	s_setprio 0
	s_setprio 1
	v_mfma_f32_16x16x32_bf16 v[52:55], v[160:163], v[182:185], v[52:55]
	v_mfma_f32_16x16x32_bf16 v[44:47], v[174:177], v[182:185], v[44:47]
	v_mfma_f32_16x16x32_bf16 v[32:35], v[174:177], v[190:193], v[32:35]
	v_mfma_f32_16x16x32_bf16 v[36:39], v[160:163], v[190:193], v[36:39]
	v_mfma_f32_16x16x32_bf16 v[16:19], v[160:163], v[198:201], v[16:19]
	v_mfma_f32_16x16x32_bf16 v[8:11], v[174:177], v[198:201], v[8:11]
	v_mfma_f32_16x16x32_bf16 v[0:3], v[174:177], v[206:209], v[0:3]
	v_mfma_f32_16x16x32_bf16 v[4:7], v[160:163], v[206:209], v[4:7]
	v_mfma_f32_16x16x32_bf16 v[52:55], v[170:173], v[186:189], v[52:55]
	v_mfma_f32_16x16x32_bf16 v[44:47], v[178:181], v[186:189], v[44:47]
	v_mfma_f32_16x16x32_bf16 v[32:35], v[178:181], v[194:197], v[32:35]
	v_mfma_f32_16x16x32_bf16 v[36:39], v[170:173], v[194:197], v[36:39]
	v_mfma_f32_16x16x32_bf16 v[16:19], v[170:173], v[202:205], v[16:19]
	v_mfma_f32_16x16x32_bf16 v[8:11], v[178:181], v[202:205], v[8:11]
	v_mfma_f32_16x16x32_bf16 v[0:3], v[178:181], v[210:213], v[0:3]
	v_mfma_f32_16x16x32_bf16 v[4:7], v[170:173], v[210:213], v[4:7]
	s_setprio 0
	s_barrier
	s_add_i32 s57, s57, 2
	s_add_u32 s55, s55, 0x100
	s_addc_u32 s56, s56, 0
	s_cmpk_gt_u32 s57, 0xa9
	s_mov_b64 s[14:15], s[16:17]
	s_cbranch_scc0 .LBB0_2165
	s_and_b64 vcc, exec, s[10:11]
	s_cbranch_vccz .LBB0_2168
	s_barrier
